# GEMM K-loops: 8 of 16 LDS-DMA per iteration switched to SGPR-base + 32-bit VGPR offset form (removes 8 v_lshl_add_u64 per iteration from the loader half); plus combine batching and prologue readback p
# speedup vs baseline: 1.0052x; 1.0036x over previous
; #define PG8_STAGE(bufoff, gbase, voff) do { _Pragma("unroll") for (int _i = 0; _i < 2; ++_i) \
;         __builtin_amdgcn_global_load_lds((const unsigned*)((const char*)(gbase) + (voff)[_i]), (PG8_LAS unsigned*)(lds + (bufoff) + ldsw + _i * 8192), 16, 0, 0); } while (0)
; #define PG8_LDA(dst, b, h) do { _Pragma("unroll") for (int m = 0; m < 4; ++m) _Pragma("unroll") for (int k = 0; k < 2; ++k) dst[m][k] = *(const PG8_LAS bf16x8*)(lds + PG8_SA(b, h) + aoff + m * 2048 + k * 1024); } while (0)
; #define PG8_LDB(dst, b, h) do { _Pragma("unroll") for (int n = 0; n < 2; ++n) _Pragma("unroll") for (int k = 0; k < 2; ++k) dst[n][k] = *(const PG8_LAS bf16x8*)(lds + PG8_SB(b, h) + boff + n * 2048 + k * 1024); } while (0)
; #define PG8_MMA(ai, bj, At, Bt) do { __builtin_amdgcn_s_setprio(1); _Pragma("unroll") for (int m = 0; m < 4; ++m) _Pragma("unroll") for (int n = 0; n < 2; ++n) _Pragma("unroll") for (int k = 0; k < 2; ++k) \
;         acc[ai][bj][m][n] = __builtin_amdgcn_mfma_f32_16x16x32_bf16(Bt[n][k], At[m][k], acc[ai][bj][m][n], 0, 0, 0); __builtin_amdgcn_s_setprio(0); } while (0)
; #define PG8_WAIT_V(n) asm volatile("s_waitcnt vmcnt(" #n ")" ::: "memory")
; #define PG8_WAIT_L(n) asm volatile("s_waitcnt lgkmcnt(" #n ")" ::: "memory")
; template <class Epi, class Sched, bool ALIGN_EPI = false, bool SP2 = false>
; __device__ __forceinline__ void gemm_phase(PG8_LAS unsigned char* lds, const Gemm g, const Sched& S, const Epi& E) {
;     ...
;             const bool last = (t == nt - 2);
;             const char* a1 = cA + (size_t)(t + 1) * kstep;
;             const char* a2 = last ? nA : cA + (size_t)(t + 2) * kstep; const char* b2 = last ? nB : cB + (size_t)(t + 2) * kstep;
;             const char* a3 = a2 + kstep; const char* b3 = b2 + kstep;
;             if (last && has_next) S.a_ready(nxt);
;             if constexpr (SP2) {
;             PG8_LDB(B0, 0, 0); PG8_LDB(B1, 0, 1); PG8_SCHED; PG8_LDA(At, 0, 0); PG8_STAGE(PG8_SA(1, 1), a1 + hstep, voffA);
;             PG8_WAIT_V(8); PG8_WAIT_L(0); PG8_BAR; PG8_MMA(0, 0, At, B0); PG8_MMA(0, 1, At, B1); PG8_BAR; PG8_SCHED;
;             PG8_LDA(At, 0, 1); PG8_STAGE(PG8_SB(0, 0), b2, voffB); PG8_STAGE(PG8_SB(0, 1), b2 + hstep, voffB); PG8_STAGE(PG8_SA(0, 0), a2, voffA);
;             PG8_WAIT_V(8); PG8_WAIT_L(0); PG8_BAR; PG8_MMA(1, 0, At, B0); PG8_MMA(1, 1, At, B1); PG8_BAR; PG8_SCHED;
.LBB0_85:
	s_add_u32 s20, s18, 0xfff80080
	s_addc_u32 s21, s19, -1
	s_add_i32 s56, 0, 0x10000
	s_cmp_eq_u32 s51, 28
	s_cselect_b32 s23, s11, s21
	s_cselect_b32 s22, s42, s20
	v_add_u32_e32 v150, s56, v153
	s_cselect_b32 s21, s9, s50
	s_cselect_b32 s20, s44, s45
	s_add_i32 s63, 0, 0x14000
	ds_read_b128 v[184:187], v150
	ds_read_b128 v[188:191], v150 offset:1024
	ds_read_b128 v[192:195], v150 offset:2048
	ds_read_b128 v[196:199], v150 offset:3072
	v_add_u32_e32 v150, s63, v153
	ds_read_b128 v[200:203], v150
	ds_read_b128 v[204:207], v150 offset:1024
	ds_read_b128 v[208:211], v150 offset:2048
	ds_read_b128 v[212:215], v150 offset:3072
	s_add_i32 m0, s27, 0xc000
	ds_read_b128 v[216:219], v155
	ds_read_b128 v[220:223], v155 offset:1024
	ds_read_b128 v[224:227], v155 offset:2048
	ds_read_b128 v[228:231], v155 offset:3072
	ds_read_b128 v[232:235], v155 offset:4096
	ds_read_b128 v[236:239], v155 offset:5120
	ds_read_b128 v[240:243], v155 offset:6144
	ds_read_b128 v[244:247], v155 offset:7168
	global_load_lds_dwordx4 v136, s[18:19]
	s_add_i32 m0, s27, 0xe000
	s_nop 0
	global_load_lds_dwordx4 v138, s[18:19]
	s_waitcnt vmcnt(8)
	s_waitcnt lgkmcnt(0)
	s_barrier
	s_setprio 1
	s_waitcnt lgkmcnt(0)
	v_mfma_f32_16x16x32_bf16 v[128:131], v[184:187], v[216:219], v[128:131]
	v_mfma_f32_16x16x32_bf16 v[120:123], v[192:195], v[216:219], v[120:123]
	v_mfma_f32_16x16x32_bf16 v[112:115], v[184:187], v[224:227], v[112:115]
	v_mfma_f32_16x16x32_bf16 v[104:107], v[192:195], v[224:227], v[104:107]
	v_mfma_f32_16x16x32_bf16 v[96:99], v[184:187], v[232:235], v[96:99]
	v_mfma_f32_16x16x32_bf16 v[88:91], v[192:195], v[232:235], v[88:91]
	v_mfma_f32_16x16x32_bf16 v[80:83], v[184:187], v[240:243], v[80:83]
	v_mfma_f32_16x16x32_bf16 v[72:75], v[192:195], v[240:243], v[72:75]
	v_mfma_f32_16x16x32_bf16 v[128:131], v[188:191], v[220:223], v[128:131]
	v_mfma_f32_16x16x32_bf16 v[120:123], v[196:199], v[220:223], v[120:123]
	v_mfma_f32_16x16x32_bf16 v[112:115], v[188:191], v[228:231], v[112:115]
	v_mfma_f32_16x16x32_bf16 v[104:107], v[196:199], v[228:231], v[104:107]
	v_mfma_f32_16x16x32_bf16 v[96:99], v[188:191], v[236:239], v[96:99]
	v_mfma_f32_16x16x32_bf16 v[88:91], v[196:199], v[236:239], v[88:91]
	v_mfma_f32_16x16x32_bf16 v[80:83], v[188:191], v[244:247], v[80:83]
	v_mfma_f32_16x16x32_bf16 v[72:75], v[196:199], v[244:247], v[72:75]
	s_setprio 0
	s_setprio 1
	v_mfma_f32_16x16x32_bf16 v[124:127], v[200:203], v[216:219], v[124:127]
	v_mfma_f32_16x16x32_bf16 v[116:119], v[208:211], v[216:219], v[116:119]
	v_mfma_f32_16x16x32_bf16 v[108:111], v[200:203], v[224:227], v[108:111]
	v_mfma_f32_16x16x32_bf16 v[100:103], v[208:211], v[224:227], v[100:103]
	v_mfma_f32_16x16x32_bf16 v[92:95], v[200:203], v[232:235], v[92:95]
	v_mfma_f32_16x16x32_bf16 v[84:87], v[208:211], v[232:235], v[84:87]
	v_mfma_f32_16x16x32_bf16 v[76:79], v[200:203], v[240:243], v[76:79]
	v_mfma_f32_16x16x32_bf16 v[68:71], v[208:211], v[240:243], v[68:71]
	v_mfma_f32_16x16x32_bf16 v[124:127], v[204:207], v[220:223], v[124:127]
	v_mfma_f32_16x16x32_bf16 v[116:119], v[212:215], v[220:223], v[116:119]
	v_mfma_f32_16x16x32_bf16 v[108:111], v[204:207], v[228:231], v[108:111]
	v_mfma_f32_16x16x32_bf16 v[100:103], v[212:215], v[228:231], v[100:103]
	v_mfma_f32_16x16x32_bf16 v[92:95], v[204:207], v[236:239], v[92:95]
	v_mfma_f32_16x16x32_bf16 v[84:87], v[212:215], v[236:239], v[84:87]
	v_mfma_f32_16x16x32_bf16 v[76:79], v[204:207], v[244:247], v[76:79]
	v_mfma_f32_16x16x32_bf16 v[68:71], v[212:215], v[244:247], v[68:71]
	s_setprio 0
	s_barrier
	s_add_i32 s56, s56, s25
	v_lshl_add_u64 v[150:151], s[20:21], 0, v[2:3]
	s_mov_b32 m0, s56
	ds_read_b128 v[216:219], v155 offset:16384
	ds_read_b128 v[220:223], v155 offset:17408
	ds_read_b128 v[224:227], v155 offset:18432
	ds_read_b128 v[228:231], v155 offset:19456
	ds_read_b128 v[232:235], v155 offset:20480
	ds_read_b128 v[236:239], v155 offset:21504
	ds_read_b128 v[240:243], v155 offset:22528
	ds_read_b128 v[244:247], v155 offset:23552
	global_load_lds_dwordx4 v[150:151], off
	s_add_i32 m0, s56, 0x2000
	s_add_u32 s56, s20, 0x80000
	v_lshl_add_u64 v[248:249], s[20:21], 0, v[0:1]
	s_addc_u32 s57, s21, 0
	s_add_i32 s63, s63, s25
	global_load_lds_dwordx4 v[248:249], off
	s_mov_b32 m0, s63
	v_lshl_add_u64 v[252:253], s[22:23], 0, v[132:133]
	global_load_lds_dwordx4 v2, s[56:57]
	s_add_i32 m0, s63, 0x2000
	s_nop 0
	global_load_lds_dwordx4 v0, s[56:57]
	v_lshl_add_u64 v[250:251], s[22:23], 0, v[134:135]
	s_mov_b32 m0, s27
	s_nop 0
	global_load_lds_dwordx4 v[250:251], off
	s_mov_b32 m0, s28
	s_nop 0
	global_load_lds_dwordx4 v[252:253], off
	s_waitcnt vmcnt(8)
	s_waitcnt lgkmcnt(0)
	s_barrier
; #define PG8_STAGE(bufoff, gbase, voff) do { _Pragma("unroll") for (int _i = 0; _i < 2; ++_i) \
;         __builtin_amdgcn_global_load_lds((const unsigned*)((const char*)(gbase) + (voff)[_i]), (PG8_LAS unsigned*)(lds + (bufoff) + ldsw + _i * 8192), 16, 0, 0); } while (0)
; #define PG8_LDA(dst, b, h) do { _Pragma("unroll") for (int m = 0; m < 4; ++m) _Pragma("unroll") for (int k = 0; k < 2; ++k) dst[m][k] = *(const PG8_LAS bf16x8*)(lds + PG8_SA(b, h) + aoff + m * 2048 + k * 1024); } while (0)
; #define PG8_LDB(dst, b, h) do { _Pragma("unroll") for (int n = 0; n < 2; ++n) _Pragma("unroll") for (int k = 0; k < 2; ++k) dst[n][k] = *(const PG8_LAS bf16x8*)(lds + PG8_SB(b, h) + boff + n * 2048 + k * 1024); } while (0)
; #define PG8_MMA(ai, bj, At, Bt) do { __builtin_amdgcn_s_setprio(1); _Pragma("unroll") for (int m = 0; m < 4; ++m) _Pragma("unroll") for (int n = 0; n < 2; ++n) _Pragma("unroll") for (int k = 0; k < 2; ++k) \
;         acc[ai][bj][m][n] = __builtin_amdgcn_mfma_f32_16x16x32_bf16(Bt[n][k], At[m][k], acc[ai][bj][m][n], 0, 0, 0); __builtin_amdgcn_s_setprio(0); } while (0)
; #define PG8_WAIT_V(n) asm volatile("s_waitcnt vmcnt(" #n ")" ::: "memory")
; #define PG8_WAIT_L(n) asm volatile("s_waitcnt lgkmcnt(" #n ")" ::: "memory")
; #define PG8_BAR __builtin_amdgcn_s_barrier()
; #define PG8_SCHED __builtin_amdgcn_sched_barrier(0)
; template <class Epi, class Sched, bool ALIGN_EPI = false, bool SP2 = false>
; __device__ __forceinline__ void gemm_phase(PG8_LAS unsigned char* lds, const Gemm g, const Sched& S, const Epi& E) {
;     ...
;             PG8_WAIT_V(8); PG8_WAIT_L(0); PG8_BAR; PG8_MMA(1, 0, At, B0); PG8_MMA(1, 1, At, B1); PG8_BAR; PG8_SCHED;
;             PG8_LDB(B0, 1, 0); PG8_LDB(B1, 1, 1); PG8_SCHED; PG8_LDA(At, 1, 0); PG8_STAGE(PG8_SA(0, 1), a2 + hstep, voffA);
;             PG8_WAIT_V(8); PG8_WAIT_L(0); PG8_BAR; PG8_MMA(0, 0, At, B0); PG8_MMA(0, 1, At, B1); PG8_BAR; PG8_SCHED;
	s_setprio 1
	s_waitcnt lgkmcnt(0)
	v_mfma_f32_16x16x32_bf16 v[64:67], v[184:187], v[216:219], v[64:67]
	v_mfma_f32_16x16x32_bf16 v[56:59], v[192:195], v[216:219], v[56:59]
	v_mfma_f32_16x16x32_bf16 v[48:51], v[184:187], v[224:227], v[48:51]
	v_mfma_f32_16x16x32_bf16 v[40:43], v[192:195], v[224:227], v[40:43]
	v_mfma_f32_16x16x32_bf16 v[32:35], v[184:187], v[232:235], v[32:35]
	v_mfma_f32_16x16x32_bf16 v[24:27], v[192:195], v[232:235], v[24:27]
	v_mfma_f32_16x16x32_bf16 v[16:19], v[184:187], v[240:243], v[16:19]
	v_mfma_f32_16x16x32_bf16 v[8:11], v[192:195], v[240:243], v[8:11]
	v_mfma_f32_16x16x32_bf16 v[64:67], v[188:191], v[220:223], v[64:67]
	v_mfma_f32_16x16x32_bf16 v[56:59], v[196:199], v[220:223], v[56:59]
	v_mfma_f32_16x16x32_bf16 v[48:51], v[188:191], v[228:231], v[48:51]
	v_mfma_f32_16x16x32_bf16 v[40:43], v[196:199], v[228:231], v[40:43]
	v_mfma_f32_16x16x32_bf16 v[32:35], v[188:191], v[236:239], v[32:35]
	v_mfma_f32_16x16x32_bf16 v[24:27], v[196:199], v[236:239], v[24:27]
	v_mfma_f32_16x16x32_bf16 v[16:19], v[188:191], v[244:247], v[16:19]
	v_mfma_f32_16x16x32_bf16 v[8:11], v[196:199], v[244:247], v[8:11]
	s_setprio 0
	s_setprio 1
	v_mfma_f32_16x16x32_bf16 v[60:63], v[200:203], v[216:219], v[60:63]
	v_mfma_f32_16x16x32_bf16 v[52:55], v[208:211], v[216:219], v[52:55]
	v_mfma_f32_16x16x32_bf16 v[44:47], v[200:203], v[224:227], v[44:47]
	v_mfma_f32_16x16x32_bf16 v[36:39], v[208:211], v[224:227], v[36:39]
	v_mfma_f32_16x16x32_bf16 v[28:31], v[200:203], v[232:235], v[28:31]
	v_mfma_f32_16x16x32_bf16 v[20:23], v[208:211], v[232:235], v[20:23]
	v_mfma_f32_16x16x32_bf16 v[12:15], v[200:203], v[240:243], v[12:15]
	v_mfma_f32_16x16x32_bf16 v[4:7], v[208:211], v[240:243], v[4:7]
	v_mfma_f32_16x16x32_bf16 v[60:63], v[204:207], v[220:223], v[60:63]
	v_mfma_f32_16x16x32_bf16 v[52:55], v[212:215], v[220:223], v[52:55]
	v_mfma_f32_16x16x32_bf16 v[44:47], v[204:207], v[228:231], v[44:47]
	v_mfma_f32_16x16x32_bf16 v[36:39], v[212:215], v[228:231], v[36:39]
	v_mfma_f32_16x16x32_bf16 v[28:31], v[204:207], v[236:239], v[28:31]
	v_mfma_f32_16x16x32_bf16 v[20:23], v[212:215], v[236:239], v[20:23]
	v_mfma_f32_16x16x32_bf16 v[12:15], v[204:207], v[244:247], v[12:15]
	v_mfma_f32_16x16x32_bf16 v[4:7], v[212:215], v[244:247], v[4:7]
	s_setprio 0
	s_barrier
	s_add_i32 s56, 0, 0x18000
	v_add_u32_e32 v161, s56, v153
	s_add_i32 s57, 0, 0x1c000
	ds_read_b128 v[184:187], v161
	ds_read_b128 v[188:191], v161 offset:1024
	ds_read_b128 v[192:195], v161 offset:2048
	ds_read_b128 v[196:199], v161 offset:3072
	v_add_u32_e32 v161, s57, v153
	ds_read_b128 v[200:203], v161
	ds_read_b128 v[204:207], v161 offset:1024
	ds_read_b128 v[208:211], v161 offset:2048
	ds_read_b128 v[212:215], v161 offset:3072
	s_add_u32 s22, s22, 0x80000
	s_addc_u32 s23, s23, 0
	s_mov_b32 m0, s29
	ds_read_b128 v[216:219], v155 offset:32768
	ds_read_b128 v[220:223], v155 offset:33792
	ds_read_b128 v[224:227], v155 offset:34816
	ds_read_b128 v[228:231], v155 offset:35840
	ds_read_b128 v[232:235], v155 offset:36864
	ds_read_b128 v[236:239], v155 offset:37888
	ds_read_b128 v[240:243], v155 offset:38912
	ds_read_b128 v[244:247], v155 offset:39936
	global_load_lds_dwordx4 v134, s[22:23]
	s_mov_b32 m0, s30
	s_nop 0
	global_load_lds_dwordx4 v132, s[22:23]
	s_waitcnt vmcnt(8)
	s_waitcnt lgkmcnt(0)
	s_barrier
	s_setprio 1
	s_waitcnt lgkmcnt(0)
	v_mfma_f32_16x16x32_bf16 v[128:131], v[184:187], v[216:219], v[128:131]
	v_mfma_f32_16x16x32_bf16 v[120:123], v[192:195], v[216:219], v[120:123]
	v_mfma_f32_16x16x32_bf16 v[112:115], v[184:187], v[224:227], v[112:115]
	v_mfma_f32_16x16x32_bf16 v[104:107], v[192:195], v[224:227], v[104:107]
	v_mfma_f32_16x16x32_bf16 v[96:99], v[184:187], v[232:235], v[96:99]
	v_mfma_f32_16x16x32_bf16 v[88:91], v[192:195], v[232:235], v[88:91]
	v_mfma_f32_16x16x32_bf16 v[80:83], v[184:187], v[240:243], v[80:83]
	v_mfma_f32_16x16x32_bf16 v[72:75], v[192:195], v[240:243], v[72:75]
	v_mfma_f32_16x16x32_bf16 v[128:131], v[188:191], v[220:223], v[128:131]
	v_mfma_f32_16x16x32_bf16 v[120:123], v[196:199], v[220:223], v[120:123]
	v_mfma_f32_16x16x32_bf16 v[112:115], v[188:191], v[228:231], v[112:115]
	v_mfma_f32_16x16x32_bf16 v[104:107], v[196:199], v[228:231], v[104:107]
	v_mfma_f32_16x16x32_bf16 v[96:99], v[188:191], v[236:239], v[96:99]
	v_mfma_f32_16x16x32_bf16 v[88:91], v[196:199], v[236:239], v[88:91]
	v_mfma_f32_16x16x32_bf16 v[80:83], v[188:191], v[244:247], v[80:83]
	v_mfma_f32_16x16x32_bf16 v[72:75], v[196:199], v[244:247], v[72:75]
	s_setprio 0
	s_setprio 1
	v_mfma_f32_16x16x32_bf16 v[124:127], v[200:203], v[216:219], v[124:127]
	v_mfma_f32_16x16x32_bf16 v[116:119], v[208:211], v[216:219], v[116:119]
	v_mfma_f32_16x16x32_bf16 v[108:111], v[200:203], v[224:227], v[108:111]
	v_mfma_f32_16x16x32_bf16 v[100:103], v[208:211], v[224:227], v[100:103]
	v_mfma_f32_16x16x32_bf16 v[92:95], v[200:203], v[232:235], v[92:95]
	v_mfma_f32_16x16x32_bf16 v[84:87], v[208:211], v[232:235], v[84:87]
	v_mfma_f32_16x16x32_bf16 v[76:79], v[200:203], v[240:243], v[76:79]
	v_mfma_f32_16x16x32_bf16 v[68:71], v[208:211], v[240:243], v[68:71]
	v_mfma_f32_16x16x32_bf16 v[124:127], v[204:207], v[220:223], v[124:127]
	v_mfma_f32_16x16x32_bf16 v[116:119], v[212:215], v[220:223], v[116:119]
	v_mfma_f32_16x16x32_bf16 v[108:111], v[204:207], v[228:231], v[108:111]
	v_mfma_f32_16x16x32_bf16 v[100:103], v[212:215], v[228:231], v[100:103]
	v_mfma_f32_16x16x32_bf16 v[92:95], v[204:207], v[236:239], v[92:95]
	v_mfma_f32_16x16x32_bf16 v[84:87], v[212:215], v[236:239], v[84:87]
	v_mfma_f32_16x16x32_bf16 v[76:79], v[204:207], v[244:247], v[76:79]
	v_mfma_f32_16x16x32_bf16 v[68:71], v[212:215], v[244:247], v[68:71]
	s_setprio 0
	s_barrier
; #define PG8_STAGE(bufoff, gbase, voff) do { _Pragma("unroll") for (int _i = 0; _i < 2; ++_i) \
;         __builtin_amdgcn_global_load_lds((const unsigned*)((const char*)(gbase) + (voff)[_i]), (PG8_LAS unsigned*)(lds + (bufoff) + ldsw + _i * 8192), 16, 0, 0); } while (0)
; #define PG8_LDA(dst, b, h) do { _Pragma("unroll") for (int m = 0; m < 4; ++m) _Pragma("unroll") for (int k = 0; k < 2; ++k) dst[m][k] = *(const PG8_LAS bf16x8*)(lds + PG8_SA(b, h) + aoff + m * 2048 + k * 1024); } while (0)
; #define PG8_MMA(ai, bj, At, Bt) do { __builtin_amdgcn_s_setprio(1); _Pragma("unroll") for (int m = 0; m < 4; ++m) _Pragma("unroll") for (int n = 0; n < 2; ++n) _Pragma("unroll") for (int k = 0; k < 2; ++k) \
;         acc[ai][bj][m][n] = __builtin_amdgcn_mfma_f32_16x16x32_bf16(Bt[n][k], At[m][k], acc[ai][bj][m][n], 0, 0, 0); __builtin_amdgcn_s_setprio(0); } while (0)
; #define PG8_WAIT_V(n) asm volatile("s_waitcnt vmcnt(" #n ")" ::: "memory")
; #define PG8_WAIT_L(n) asm volatile("s_waitcnt lgkmcnt(" #n ")" ::: "memory")
; #define PG8_BAR __builtin_amdgcn_s_barrier()
; #define PG8_SCHED __builtin_amdgcn_sched_barrier(0)
; template <class Epi, class Sched, bool ALIGN_EPI = false, bool SP2 = false>
; __device__ __forceinline__ void gemm_phase(PG8_LAS unsigned char* lds, const Gemm g, const Sched& S, const Epi& E) {
;     ...
;             PG8_LDA(At, 1, 1); PG8_STAGE(PG8_SB(1, 0), b3, voffB); PG8_STAGE(PG8_SB(1, 1), b3 + hstep, voffB); PG8_STAGE(PG8_SA(1, 0), a3, voffA);
;             PG8_WAIT_V(8); PG8_WAIT_L(0); PG8_BAR; PG8_MMA(1, 0, At, B0); PG8_MMA(1, 1, At, B1); PG8_BAR; PG8_SCHED;
;     ...
;         if constexpr (ALIGN_EPI) { if (wr == 0) PG8_BAR; }
	s_add_i32 s22, s56, s25
	v_lshl_add_u64 v[150:151], v[150:151], 0, s[36:37]
	s_mov_b32 m0, s22
	ds_read_b128 v[216:219], v155 offset:49152
	ds_read_b128 v[220:223], v155 offset:50176
	ds_read_b128 v[224:227], v155 offset:51200
	ds_read_b128 v[228:231], v155 offset:52224
	ds_read_b128 v[232:235], v155 offset:53248
	ds_read_b128 v[236:239], v155 offset:54272
	ds_read_b128 v[240:243], v155 offset:55296
	ds_read_b128 v[244:247], v155 offset:56320
	global_load_lds_dwordx4 v[150:151], off
	s_add_i32 m0, s22, 0x2000
	s_add_u32 s20, s20, 0x80080
	v_lshl_add_u64 v[150:151], v[248:249], 0, s[36:37]
	s_addc_u32 s21, s21, 0
	s_add_i32 s22, s57, s25
	global_load_lds_dwordx4 v[150:151], off
	s_mov_b32 m0, s22
	s_nop 0
	global_load_lds_dwordx4 v2, s[20:21]
	s_add_i32 m0, s22, 0x2000
	s_nop 0
	global_load_lds_dwordx4 v0, s[20:21]
	v_lshl_add_u64 v[150:151], v[250:251], 0, s[36:37]
	s_mov_b32 m0, s31
	s_nop 0
	global_load_lds_dwordx4 v[150:151], off
	v_lshl_add_u64 v[150:151], v[252:253], 0, s[36:37]
	s_mov_b32 m0, s34
	s_nop 0
	global_load_lds_dwordx4 v[150:151], off
	s_waitcnt vmcnt(8)
	s_waitcnt lgkmcnt(0)
	s_barrier
	s_setprio 1
	s_waitcnt lgkmcnt(0)
	v_mfma_f32_16x16x32_bf16 v[64:67], v[184:187], v[216:219], v[64:67]
	v_mfma_f32_16x16x32_bf16 v[56:59], v[192:195], v[216:219], v[56:59]
	v_mfma_f32_16x16x32_bf16 v[48:51], v[184:187], v[224:227], v[48:51]
	v_mfma_f32_16x16x32_bf16 v[40:43], v[192:195], v[224:227], v[40:43]
	v_mfma_f32_16x16x32_bf16 v[32:35], v[184:187], v[232:235], v[32:35]
	v_mfma_f32_16x16x32_bf16 v[24:27], v[192:195], v[232:235], v[24:27]
	v_mfma_f32_16x16x32_bf16 v[16:19], v[184:187], v[240:243], v[16:19]
	v_mfma_f32_16x16x32_bf16 v[8:11], v[192:195], v[240:243], v[8:11]
	v_mfma_f32_16x16x32_bf16 v[64:67], v[188:191], v[220:223], v[64:67]
	v_mfma_f32_16x16x32_bf16 v[56:59], v[196:199], v[220:223], v[56:59]
	v_mfma_f32_16x16x32_bf16 v[48:51], v[188:191], v[228:231], v[48:51]
	v_mfma_f32_16x16x32_bf16 v[40:43], v[196:199], v[228:231], v[40:43]
	v_mfma_f32_16x16x32_bf16 v[32:35], v[188:191], v[236:239], v[32:35]
	v_mfma_f32_16x16x32_bf16 v[24:27], v[196:199], v[236:239], v[24:27]
	v_mfma_f32_16x16x32_bf16 v[16:19], v[188:191], v[244:247], v[16:19]
	v_mfma_f32_16x16x32_bf16 v[8:11], v[196:199], v[244:247], v[8:11]
	s_setprio 0
	s_setprio 1
	v_mfma_f32_16x16x32_bf16 v[60:63], v[200:203], v[216:219], v[60:63]
	v_mfma_f32_16x16x32_bf16 v[52:55], v[208:211], v[216:219], v[52:55]
	v_mfma_f32_16x16x32_bf16 v[44:47], v[200:203], v[224:227], v[44:47]
	v_mfma_f32_16x16x32_bf16 v[36:39], v[208:211], v[224:227], v[36:39]
	v_mfma_f32_16x16x32_bf16 v[28:31], v[200:203], v[232:235], v[28:31]
	v_mfma_f32_16x16x32_bf16 v[20:23], v[208:211], v[232:235], v[20:23]
	v_mfma_f32_16x16x32_bf16 v[12:15], v[200:203], v[240:243], v[12:15]
	v_mfma_f32_16x16x32_bf16 v[4:7], v[208:211], v[240:243], v[4:7]
	v_mfma_f32_16x16x32_bf16 v[60:63], v[204:207], v[220:223], v[60:63]
	v_mfma_f32_16x16x32_bf16 v[52:55], v[212:215], v[220:223], v[52:55]
	v_mfma_f32_16x16x32_bf16 v[44:47], v[204:207], v[228:231], v[44:47]
	v_mfma_f32_16x16x32_bf16 v[36:39], v[212:215], v[228:231], v[36:39]
	v_mfma_f32_16x16x32_bf16 v[28:31], v[204:207], v[236:239], v[28:31]
	v_mfma_f32_16x16x32_bf16 v[20:23], v[212:215], v[236:239], v[20:23]
	v_mfma_f32_16x16x32_bf16 v[12:15], v[204:207], v[244:247], v[12:15]
	v_mfma_f32_16x16x32_bf16 v[4:7], v[212:215], v[244:247], v[4:7]
	s_setprio 0
	s_barrier
	s_add_i32 s51, s51, 2
	s_add_u32 s18, s18, 0x100
	s_addc_u32 s19, s19, 0
	s_add_u32 s45, s45, 0x100
	s_addc_u32 s50, s50, 0
	s_cmp_gt_u32 s51, 29
	s_cbranch_scc0 .LBB0_85
	s_and_b64 vcc, exec, s[6:7]
	s_cbranch_vccz .LBB0_88
	s_barrier

; #define PG8_STAGE(bufoff, gbase, voff) do { _Pragma("unroll") for (int _i = 0; _i < 2; ++_i) \
;         __builtin_amdgcn_global_load_lds((const unsigned*)((const char*)(gbase) + (voff)[_i]), (PG8_LAS unsigned*)(lds + (bufoff) + ldsw + _i * 8192), 16, 0, 0); } while (0)
; #define PG8_LDA(dst, b, h) do { _Pragma("unroll") for (int m = 0; m < 4; ++m) _Pragma("unroll") for (int k = 0; k < 2; ++k) dst[m][k] = *(const PG8_LAS bf16x8*)(lds + PG8_SA(b, h) + aoff + m * 2048 + k * 1024); } while (0)
; #define PG8_LDB(dst, b, h) do { _Pragma("unroll") for (int n = 0; n < 2; ++n) _Pragma("unroll") for (int k = 0; k < 2; ++k) dst[n][k] = *(const PG8_LAS bf16x8*)(lds + PG8_SB(b, h) + boff + n * 2048 + k * 1024); } while (0)
; #define PG8_MMA(ai, bj, At, Bt) do { __builtin_amdgcn_s_setprio(1); _Pragma("unroll") for (int m = 0; m < 4; ++m) _Pragma("unroll") for (int n = 0; n < 2; ++n) _Pragma("unroll") for (int k = 0; k < 2; ++k) \
;         acc[ai][bj][m][n] = __builtin_amdgcn_mfma_f32_16x16x32_bf16(Bt[n][k], At[m][k], acc[ai][bj][m][n], 0, 0, 0); __builtin_amdgcn_s_setprio(0); } while (0)
; #define PG8_WAIT_V(n) asm volatile("s_waitcnt vmcnt(" #n ")" ::: "memory")
; #define PG8_WAIT_L(n) asm volatile("s_waitcnt lgkmcnt(" #n ")" ::: "memory")
; template <class Epi, class Sched, bool ALIGN_EPI = false, bool SP2 = false>
; __device__ __forceinline__ void gemm_phase(PG8_LAS unsigned char* lds, const Gemm g, const Sched& S, const Epi& E) {
;     ...
;             const bool last = (t == nt - 2);
;             const char* a1 = cA + (size_t)(t + 1) * kstep;
;             const char* a2 = last ? nA : cA + (size_t)(t + 2) * kstep; const char* b2 = last ? nB : cB + (size_t)(t + 2) * kstep;
;             const char* a3 = a2 + kstep; const char* b3 = b2 + kstep;
;             if (last && has_next) S.a_ready(nxt);
;             if constexpr (SP2) {
;             PG8_LDB(B0, 0, 0); PG8_LDB(B1, 0, 1); PG8_SCHED; PG8_LDA(At, 0, 0); PG8_STAGE(PG8_SA(1, 1), a1 + hstep, voffA);
;             PG8_WAIT_V(8); PG8_WAIT_L(0); PG8_BAR; PG8_MMA(0, 0, At, B0); PG8_MMA(0, 1, At, B1); PG8_BAR; PG8_SCHED;
;             PG8_LDA(At, 0, 1); PG8_STAGE(PG8_SB(0, 0), b2, voffB); PG8_STAGE(PG8_SB(0, 1), b2 + hstep, voffB); PG8_STAGE(PG8_SA(0, 0), a2, voffA);
;             PG8_WAIT_V(8); PG8_WAIT_L(0); PG8_BAR; PG8_MMA(1, 0, At, B0); PG8_MMA(1, 1, At, B1); PG8_BAR; PG8_SCHED;
.LBB0_167:
	s_add_u32 s16, s14, 0x100
	s_addc_u32 s17, s15, 0
	s_add_i32 s63, 0, 0x10000
	s_cmpk_eq_i32 s57, 0x54
	s_cselect_b32 s21, s7, s17
	s_cselect_b32 s20, s6, s16
	s_cselect_b32 s19, s13, s56
	s_cselect_b32 s18, s12, s51
	s_add_i32 s64, 0, 0x14000
	v_add_u32_e32 v162, s63, v185
	v_add_u32_e32 v166, s64, v185
	ds_read_b128 v[132:135], v162
	ds_read_b128 v[136:139], v162 offset:1024
	ds_read_b128 v[158:161], v162 offset:2048
	ds_read_b128 v[162:165], v162 offset:3072
	ds_read_b128 v[188:191], v166
	ds_read_b128 v[192:195], v166 offset:1024
	ds_read_b128 v[196:199], v166 offset:2048
	ds_read_b128 v[200:203], v166 offset:3072
	s_add_i32 m0, s26, 0xc000
	ds_read_b128 v[204:207], v187
	ds_read_b128 v[208:211], v187 offset:1024
	ds_read_b128 v[212:215], v187 offset:2048
	ds_read_b128 v[216:219], v187 offset:3072
	ds_read_b128 v[220:223], v187 offset:4096
	ds_read_b128 v[224:227], v187 offset:5120
	ds_read_b128 v[228:231], v187 offset:6144
	ds_read_b128 v[232:235], v187 offset:7168
	global_load_lds_dwordx4 v154, s[14:15]
	s_add_i32 m0, s26, 0xe000
	s_nop 0
	global_load_lds_dwordx4 v156, s[14:15]
	s_waitcnt vmcnt(8)
	s_waitcnt lgkmcnt(0)
	s_barrier
	s_setprio 1
	s_waitcnt lgkmcnt(0)
	v_mfma_f32_16x16x32_bf16 v[128:131], v[132:135], v[204:207], v[128:131]
	v_mfma_f32_16x16x32_bf16 v[124:127], v[158:161], v[204:207], v[124:127]
	v_mfma_f32_16x16x32_bf16 v[112:115], v[132:135], v[212:215], v[112:115]
	v_mfma_f32_16x16x32_bf16 v[108:111], v[158:161], v[212:215], v[108:111]
	v_mfma_f32_16x16x32_bf16 v[96:99], v[132:135], v[220:223], v[96:99]
	v_mfma_f32_16x16x32_bf16 v[92:95], v[158:161], v[220:223], v[92:95]
	v_mfma_f32_16x16x32_bf16 v[80:83], v[132:135], v[228:231], v[80:83]
	v_mfma_f32_16x16x32_bf16 v[76:79], v[158:161], v[228:231], v[76:79]
	v_mfma_f32_16x16x32_bf16 v[128:131], v[136:139], v[208:211], v[128:131]
	v_mfma_f32_16x16x32_bf16 v[124:127], v[162:165], v[208:211], v[124:127]
	v_mfma_f32_16x16x32_bf16 v[112:115], v[136:139], v[216:219], v[112:115]
	v_mfma_f32_16x16x32_bf16 v[108:111], v[162:165], v[216:219], v[108:111]
	v_mfma_f32_16x16x32_bf16 v[96:99], v[136:139], v[224:227], v[96:99]
	v_mfma_f32_16x16x32_bf16 v[92:95], v[162:165], v[224:227], v[92:95]
	v_mfma_f32_16x16x32_bf16 v[80:83], v[136:139], v[232:235], v[80:83]
	v_mfma_f32_16x16x32_bf16 v[76:79], v[162:165], v[232:235], v[76:79]
	s_setprio 0
	s_setprio 1
	v_mfma_f32_16x16x32_bf16 v[120:123], v[188:191], v[204:207], v[120:123]
	v_mfma_f32_16x16x32_bf16 v[116:119], v[196:199], v[204:207], v[116:119]
	v_mfma_f32_16x16x32_bf16 v[104:107], v[188:191], v[212:215], v[104:107]
	v_mfma_f32_16x16x32_bf16 v[100:103], v[196:199], v[212:215], v[100:103]
	v_mfma_f32_16x16x32_bf16 v[88:91], v[188:191], v[220:223], v[88:91]
	v_mfma_f32_16x16x32_bf16 v[84:87], v[196:199], v[220:223], v[84:87]
	v_mfma_f32_16x16x32_bf16 v[72:75], v[188:191], v[228:231], v[72:75]
	v_mfma_f32_16x16x32_bf16 v[68:71], v[196:199], v[228:231], v[68:71]
	v_mfma_f32_16x16x32_bf16 v[120:123], v[192:195], v[208:211], v[120:123]
	v_mfma_f32_16x16x32_bf16 v[116:119], v[200:203], v[208:211], v[116:119]
	v_mfma_f32_16x16x32_bf16 v[104:107], v[192:195], v[216:219], v[104:107]
	v_mfma_f32_16x16x32_bf16 v[100:103], v[200:203], v[216:219], v[100:103]
	v_mfma_f32_16x16x32_bf16 v[88:91], v[192:195], v[224:227], v[88:91]
	v_mfma_f32_16x16x32_bf16 v[84:87], v[200:203], v[224:227], v[84:87]
	v_mfma_f32_16x16x32_bf16 v[72:75], v[192:195], v[232:235], v[72:75]
	v_mfma_f32_16x16x32_bf16 v[68:71], v[200:203], v[232:235], v[68:71]
	s_setprio 0
	s_barrier
	s_add_i32 s14, s63, s25
	v_lshl_add_u64 v[166:167], s[18:19], 0, v[2:3]
	s_mov_b32 m0, s14
	ds_read_b128 v[204:207], v187 offset:16384
	ds_read_b128 v[208:211], v187 offset:17408
	ds_read_b128 v[212:215], v187 offset:18432
	ds_read_b128 v[216:219], v187 offset:19456
	ds_read_b128 v[220:223], v187 offset:20480
	ds_read_b128 v[224:227], v187 offset:21504
	ds_read_b128 v[228:231], v187 offset:22528
	ds_read_b128 v[232:235], v187 offset:23552
	global_load_lds_dwordx4 v[166:167], off
	s_add_i32 m0, s14, 0x2000
	s_add_u32 s14, s18, 0x160000
	v_lshl_add_u64 v[236:237], s[18:19], 0, v[152:153]
	s_addc_u32 s15, s19, 0
	s_add_i32 s63, s64, s25
	global_load_lds_dwordx4 v[236:237], off
	s_mov_b32 m0, s63
	v_lshl_add_u64 v[240:241], s[20:21], 0, v[150:151]
	global_load_lds_dwordx4 v2, s[14:15]
	s_add_i32 m0, s63, 0x2000
	s_nop 0
	global_load_lds_dwordx4 v152, s[14:15]
	v_lshl_add_u64 v[238:239], s[20:21], 0, v[0:1]
	s_mov_b32 m0, s26
	s_nop 0
	global_load_lds_dwordx4 v[238:239], off
	s_mov_b32 m0, s27
	s_nop 0
	global_load_lds_dwordx4 v[240:241], off
	s_waitcnt vmcnt(8)
	s_waitcnt lgkmcnt(0)
	s_barrier
; #define PG8_STAGE(bufoff, gbase, voff) do { _Pragma("unroll") for (int _i = 0; _i < 2; ++_i) \
;         __builtin_amdgcn_global_load_lds((const unsigned*)((const char*)(gbase) + (voff)[_i]), (PG8_LAS unsigned*)(lds + (bufoff) + ldsw + _i * 8192), 16, 0, 0); } while (0)
; #define PG8_LDA(dst, b, h) do { _Pragma("unroll") for (int m = 0; m < 4; ++m) _Pragma("unroll") for (int k = 0; k < 2; ++k) dst[m][k] = *(const PG8_LAS bf16x8*)(lds + PG8_SA(b, h) + aoff + m * 2048 + k * 1024); } while (0)
; #define PG8_LDB(dst, b, h) do { _Pragma("unroll") for (int n = 0; n < 2; ++n) _Pragma("unroll") for (int k = 0; k < 2; ++k) dst[n][k] = *(const PG8_LAS bf16x8*)(lds + PG8_SB(b, h) + boff + n * 2048 + k * 1024); } while (0)
; #define PG8_MMA(ai, bj, At, Bt) do { __builtin_amdgcn_s_setprio(1); _Pragma("unroll") for (int m = 0; m < 4; ++m) _Pragma("unroll") for (int n = 0; n < 2; ++n) _Pragma("unroll") for (int k = 0; k < 2; ++k) \
;         acc[ai][bj][m][n] = __builtin_amdgcn_mfma_f32_16x16x32_bf16(Bt[n][k], At[m][k], acc[ai][bj][m][n], 0, 0, 0); __builtin_amdgcn_s_setprio(0); } while (0)
; #define PG8_WAIT_V(n) asm volatile("s_waitcnt vmcnt(" #n ")" ::: "memory")
; #define PG8_WAIT_L(n) asm volatile("s_waitcnt lgkmcnt(" #n ")" ::: "memory")
; #define PG8_BAR __builtin_amdgcn_s_barrier()
; #define PG8_SCHED __builtin_amdgcn_sched_barrier(0)
; template <class Epi, class Sched, bool ALIGN_EPI = false, bool SP2 = false>
; __device__ __forceinline__ void gemm_phase(PG8_LAS unsigned char* lds, const Gemm g, const Sched& S, const Epi& E) {
;     ...
;             PG8_WAIT_V(8); PG8_WAIT_L(0); PG8_BAR; PG8_MMA(1, 0, At, B0); PG8_MMA(1, 1, At, B1); PG8_BAR; PG8_SCHED;
;             PG8_LDB(B0, 1, 0); PG8_LDB(B1, 1, 1); PG8_SCHED; PG8_LDA(At, 1, 0); PG8_STAGE(PG8_SA(0, 1), a2 + hstep, voffA);
;             PG8_WAIT_V(8); PG8_WAIT_L(0); PG8_BAR; PG8_MMA(0, 0, At, B0); PG8_MMA(0, 1, At, B1); PG8_BAR; PG8_SCHED;
	s_setprio 1
	s_waitcnt lgkmcnt(0)
	v_mfma_f32_16x16x32_bf16 v[64:67], v[132:135], v[204:207], v[64:67]
	v_mfma_f32_16x16x32_bf16 v[60:63], v[158:161], v[204:207], v[60:63]
	v_mfma_f32_16x16x32_bf16 v[48:51], v[132:135], v[212:215], v[48:51]
	v_mfma_f32_16x16x32_bf16 v[44:47], v[158:161], v[212:215], v[44:47]
	v_mfma_f32_16x16x32_bf16 v[32:35], v[132:135], v[220:223], v[32:35]
	v_mfma_f32_16x16x32_bf16 v[28:31], v[158:161], v[220:223], v[28:31]
	v_mfma_f32_16x16x32_bf16 v[16:19], v[132:135], v[228:231], v[16:19]
	v_mfma_f32_16x16x32_bf16 v[12:15], v[158:161], v[228:231], v[12:15]
	v_mfma_f32_16x16x32_bf16 v[64:67], v[136:139], v[208:211], v[64:67]
	v_mfma_f32_16x16x32_bf16 v[60:63], v[162:165], v[208:211], v[60:63]
	v_mfma_f32_16x16x32_bf16 v[48:51], v[136:139], v[216:219], v[48:51]
	v_mfma_f32_16x16x32_bf16 v[44:47], v[162:165], v[216:219], v[44:47]
	v_mfma_f32_16x16x32_bf16 v[32:35], v[136:139], v[224:227], v[32:35]
	v_mfma_f32_16x16x32_bf16 v[28:31], v[162:165], v[224:227], v[28:31]
	v_mfma_f32_16x16x32_bf16 v[16:19], v[136:139], v[232:235], v[16:19]
	v_mfma_f32_16x16x32_bf16 v[12:15], v[162:165], v[232:235], v[12:15]
	s_setprio 0
	s_setprio 1
	v_mfma_f32_16x16x32_bf16 v[56:59], v[188:191], v[204:207], v[56:59]
	v_mfma_f32_16x16x32_bf16 v[52:55], v[196:199], v[204:207], v[52:55]
	v_mfma_f32_16x16x32_bf16 v[40:43], v[188:191], v[212:215], v[40:43]
	v_mfma_f32_16x16x32_bf16 v[36:39], v[196:199], v[212:215], v[36:39]
	v_mfma_f32_16x16x32_bf16 v[24:27], v[188:191], v[220:223], v[24:27]
	v_mfma_f32_16x16x32_bf16 v[20:23], v[196:199], v[220:223], v[20:23]
	v_mfma_f32_16x16x32_bf16 v[8:11], v[188:191], v[228:231], v[8:11]
	v_mfma_f32_16x16x32_bf16 v[4:7], v[196:199], v[228:231], v[4:7]
	v_mfma_f32_16x16x32_bf16 v[56:59], v[192:195], v[208:211], v[56:59]
	v_mfma_f32_16x16x32_bf16 v[52:55], v[200:203], v[208:211], v[52:55]
	v_mfma_f32_16x16x32_bf16 v[40:43], v[192:195], v[216:219], v[40:43]
	v_mfma_f32_16x16x32_bf16 v[36:39], v[200:203], v[216:219], v[36:39]
	v_mfma_f32_16x16x32_bf16 v[24:27], v[192:195], v[224:227], v[24:27]
	v_mfma_f32_16x16x32_bf16 v[20:23], v[200:203], v[224:227], v[20:23]
	v_mfma_f32_16x16x32_bf16 v[8:11], v[192:195], v[232:235], v[8:11]
	v_mfma_f32_16x16x32_bf16 v[4:7], v[200:203], v[232:235], v[4:7]
	s_setprio 0
	s_barrier
	s_add_i32 s63, 0, 0x18000
	s_add_i32 s64, 0, 0x1c000
	v_add_u32_e32 v162, s63, v185
	v_add_u32_e32 v200, s64, v185
	ds_read_b128 v[132:135], v162
	ds_read_b128 v[136:139], v162 offset:1024
	ds_read_b128 v[158:161], v162 offset:2048
	ds_read_b128 v[162:165], v162 offset:3072
	ds_read_b128 v[188:191], v200
	ds_read_b128 v[192:195], v200 offset:1024
	ds_read_b128 v[196:199], v200 offset:2048
	ds_read_b128 v[200:203], v200 offset:3072
	s_add_u32 s14, s20, 0x160000
	s_addc_u32 s15, s21, 0
	s_mov_b32 m0, s28
	ds_read_b128 v[204:207], v187 offset:32768
	ds_read_b128 v[208:211], v187 offset:33792
	ds_read_b128 v[212:215], v187 offset:34816
	ds_read_b128 v[216:219], v187 offset:35840
	ds_read_b128 v[220:223], v187 offset:36864
	ds_read_b128 v[224:227], v187 offset:37888
	ds_read_b128 v[228:231], v187 offset:38912
	ds_read_b128 v[232:235], v187 offset:39936
	global_load_lds_dwordx4 v0, s[14:15]
	s_mov_b32 m0, s29
	s_nop 0
	global_load_lds_dwordx4 v150, s[14:15]
	s_waitcnt vmcnt(8)
	s_waitcnt lgkmcnt(0)
	s_barrier
	s_setprio 1
	s_waitcnt lgkmcnt(0)
	v_mfma_f32_16x16x32_bf16 v[128:131], v[132:135], v[204:207], v[128:131]
	v_mfma_f32_16x16x32_bf16 v[124:127], v[158:161], v[204:207], v[124:127]
	v_mfma_f32_16x16x32_bf16 v[112:115], v[132:135], v[212:215], v[112:115]
	v_mfma_f32_16x16x32_bf16 v[108:111], v[158:161], v[212:215], v[108:111]
	v_mfma_f32_16x16x32_bf16 v[96:99], v[132:135], v[220:223], v[96:99]
	v_mfma_f32_16x16x32_bf16 v[92:95], v[158:161], v[220:223], v[92:95]
	v_mfma_f32_16x16x32_bf16 v[80:83], v[132:135], v[228:231], v[80:83]
	v_mfma_f32_16x16x32_bf16 v[76:79], v[158:161], v[228:231], v[76:79]
	v_mfma_f32_16x16x32_bf16 v[128:131], v[136:139], v[208:211], v[128:131]
	v_mfma_f32_16x16x32_bf16 v[124:127], v[162:165], v[208:211], v[124:127]
	v_mfma_f32_16x16x32_bf16 v[112:115], v[136:139], v[216:219], v[112:115]
	v_mfma_f32_16x16x32_bf16 v[108:111], v[162:165], v[216:219], v[108:111]
	v_mfma_f32_16x16x32_bf16 v[96:99], v[136:139], v[224:227], v[96:99]
	v_mfma_f32_16x16x32_bf16 v[92:95], v[162:165], v[224:227], v[92:95]
	v_mfma_f32_16x16x32_bf16 v[80:83], v[136:139], v[232:235], v[80:83]
	v_mfma_f32_16x16x32_bf16 v[76:79], v[162:165], v[232:235], v[76:79]
	s_setprio 0
	s_setprio 1
	v_mfma_f32_16x16x32_bf16 v[120:123], v[188:191], v[204:207], v[120:123]
	v_mfma_f32_16x16x32_bf16 v[116:119], v[196:199], v[204:207], v[116:119]
	v_mfma_f32_16x16x32_bf16 v[104:107], v[188:191], v[212:215], v[104:107]
	v_mfma_f32_16x16x32_bf16 v[100:103], v[196:199], v[212:215], v[100:103]
	v_mfma_f32_16x16x32_bf16 v[88:91], v[188:191], v[220:223], v[88:91]
	v_mfma_f32_16x16x32_bf16 v[84:87], v[196:199], v[220:223], v[84:87]
	v_mfma_f32_16x16x32_bf16 v[72:75], v[188:191], v[228:231], v[72:75]
	v_mfma_f32_16x16x32_bf16 v[68:71], v[196:199], v[228:231], v[68:71]
	v_mfma_f32_16x16x32_bf16 v[120:123], v[192:195], v[208:211], v[120:123]
	v_mfma_f32_16x16x32_bf16 v[116:119], v[200:203], v[208:211], v[116:119]
	v_mfma_f32_16x16x32_bf16 v[104:107], v[192:195], v[216:219], v[104:107]
	v_mfma_f32_16x16x32_bf16 v[100:103], v[200:203], v[216:219], v[100:103]
	v_mfma_f32_16x16x32_bf16 v[88:91], v[192:195], v[224:227], v[88:91]
	v_mfma_f32_16x16x32_bf16 v[84:87], v[200:203], v[224:227], v[84:87]
	v_mfma_f32_16x16x32_bf16 v[72:75], v[192:195], v[232:235], v[72:75]
	v_mfma_f32_16x16x32_bf16 v[68:71], v[200:203], v[232:235], v[68:71]
	s_setprio 0
	s_barrier
; #define PG8_STAGE(bufoff, gbase, voff) do { _Pragma("unroll") for (int _i = 0; _i < 2; ++_i) \
;         __builtin_amdgcn_global_load_lds((const unsigned*)((const char*)(gbase) + (voff)[_i]), (PG8_LAS unsigned*)(lds + (bufoff) + ldsw + _i * 8192), 16, 0, 0); } while (0)
; #define PG8_LDA(dst, b, h) do { _Pragma("unroll") for (int m = 0; m < 4; ++m) _Pragma("unroll") for (int k = 0; k < 2; ++k) dst[m][k] = *(const PG8_LAS bf16x8*)(lds + PG8_SA(b, h) + aoff + m * 2048 + k * 1024); } while (0)
; #define PG8_MMA(ai, bj, At, Bt) do { __builtin_amdgcn_s_setprio(1); _Pragma("unroll") for (int m = 0; m < 4; ++m) _Pragma("unroll") for (int n = 0; n < 2; ++n) _Pragma("unroll") for (int k = 0; k < 2; ++k) \
;         acc[ai][bj][m][n] = __builtin_amdgcn_mfma_f32_16x16x32_bf16(Bt[n][k], At[m][k], acc[ai][bj][m][n], 0, 0, 0); __builtin_amdgcn_s_setprio(0); } while (0)
; #define PG8_WAIT_V(n) asm volatile("s_waitcnt vmcnt(" #n ")" ::: "memory")
; #define PG8_WAIT_L(n) asm volatile("s_waitcnt lgkmcnt(" #n ")" ::: "memory")
; #define PG8_BAR __builtin_amdgcn_s_barrier()
; #define PG8_SCHED __builtin_amdgcn_sched_barrier(0)
; template <class Epi, class Sched, bool ALIGN_EPI = false, bool SP2 = false>
; __device__ __forceinline__ void gemm_phase(PG8_LAS unsigned char* lds, const Gemm g, const Sched& S, const Epi& E) {
;     ...
;             PG8_LDA(At, 1, 1); PG8_STAGE(PG8_SB(1, 0), b3, voffB); PG8_STAGE(PG8_SB(1, 1), b3 + hstep, voffB); PG8_STAGE(PG8_SA(1, 0), a3, voffA);
;             PG8_WAIT_V(8); PG8_WAIT_L(0); PG8_BAR; PG8_MMA(1, 0, At, B0); PG8_MMA(1, 1, At, B1); PG8_BAR; PG8_SCHED;
;     ...
;         if constexpr (ALIGN_EPI) { if (wr == 0) PG8_BAR; }
	s_add_i32 s14, s63, s25
	v_lshl_add_u64 v[166:167], v[166:167], 0, s[36:37]
	s_mov_b32 m0, s14
	ds_read_b128 v[204:207], v187 offset:49152
	ds_read_b128 v[208:211], v187 offset:50176
	ds_read_b128 v[212:215], v187 offset:51200
	ds_read_b128 v[216:219], v187 offset:52224
	ds_read_b128 v[220:223], v187 offset:53248
	ds_read_b128 v[224:227], v187 offset:54272
	ds_read_b128 v[228:231], v187 offset:55296
	ds_read_b128 v[232:235], v187 offset:56320
	global_load_lds_dwordx4 v[166:167], off
	s_add_i32 m0, s14, 0x2000
	s_add_u32 s14, s18, 0x160080
	v_lshl_add_u64 v[166:167], v[236:237], 0, s[36:37]
	s_addc_u32 s15, s19, 0
	s_add_i32 s18, s64, s25
	global_load_lds_dwordx4 v[166:167], off
	s_mov_b32 m0, s18
	s_nop 0
	global_load_lds_dwordx4 v2, s[14:15]
	s_add_i32 m0, s18, 0x2000
	s_nop 0
	global_load_lds_dwordx4 v152, s[14:15]
	v_lshl_add_u64 v[166:167], v[238:239], 0, s[36:37]
	s_mov_b32 m0, s30
	s_nop 0
	global_load_lds_dwordx4 v[166:167], off
	v_lshl_add_u64 v[166:167], v[240:241], 0, s[36:37]
	s_mov_b32 m0, s31
	s_nop 0
	global_load_lds_dwordx4 v[166:167], off
	s_waitcnt vmcnt(8)
	s_waitcnt lgkmcnt(0)
	s_barrier
	s_setprio 1
	s_waitcnt lgkmcnt(0)
	v_mfma_f32_16x16x32_bf16 v[64:67], v[132:135], v[204:207], v[64:67]
	v_mfma_f32_16x16x32_bf16 v[60:63], v[158:161], v[204:207], v[60:63]
	v_mfma_f32_16x16x32_bf16 v[48:51], v[132:135], v[212:215], v[48:51]
	v_mfma_f32_16x16x32_bf16 v[44:47], v[158:161], v[212:215], v[44:47]
	v_mfma_f32_16x16x32_bf16 v[32:35], v[132:135], v[220:223], v[32:35]
	v_mfma_f32_16x16x32_bf16 v[28:31], v[158:161], v[220:223], v[28:31]
	v_mfma_f32_16x16x32_bf16 v[16:19], v[132:135], v[228:231], v[16:19]
	v_mfma_f32_16x16x32_bf16 v[12:15], v[158:161], v[228:231], v[12:15]
	v_mfma_f32_16x16x32_bf16 v[64:67], v[136:139], v[208:211], v[64:67]
	v_mfma_f32_16x16x32_bf16 v[60:63], v[162:165], v[208:211], v[60:63]
	v_mfma_f32_16x16x32_bf16 v[48:51], v[136:139], v[216:219], v[48:51]
	v_mfma_f32_16x16x32_bf16 v[44:47], v[162:165], v[216:219], v[44:47]
	v_mfma_f32_16x16x32_bf16 v[32:35], v[136:139], v[224:227], v[32:35]
	v_mfma_f32_16x16x32_bf16 v[28:31], v[162:165], v[224:227], v[28:31]
	v_mfma_f32_16x16x32_bf16 v[16:19], v[136:139], v[232:235], v[16:19]
	v_mfma_f32_16x16x32_bf16 v[12:15], v[162:165], v[232:235], v[12:15]
	s_setprio 0
	s_setprio 1
	v_mfma_f32_16x16x32_bf16 v[56:59], v[188:191], v[204:207], v[56:59]
	v_mfma_f32_16x16x32_bf16 v[52:55], v[196:199], v[204:207], v[52:55]
	v_mfma_f32_16x16x32_bf16 v[40:43], v[188:191], v[212:215], v[40:43]
	v_mfma_f32_16x16x32_bf16 v[36:39], v[196:199], v[212:215], v[36:39]
	v_mfma_f32_16x16x32_bf16 v[24:27], v[188:191], v[220:223], v[24:27]
	v_mfma_f32_16x16x32_bf16 v[20:23], v[196:199], v[220:223], v[20:23]
	v_mfma_f32_16x16x32_bf16 v[8:11], v[188:191], v[228:231], v[8:11]
	v_mfma_f32_16x16x32_bf16 v[4:7], v[196:199], v[228:231], v[4:7]
	v_mfma_f32_16x16x32_bf16 v[56:59], v[192:195], v[208:211], v[56:59]
	v_mfma_f32_16x16x32_bf16 v[52:55], v[200:203], v[208:211], v[52:55]
	v_mfma_f32_16x16x32_bf16 v[40:43], v[192:195], v[216:219], v[40:43]
	v_mfma_f32_16x16x32_bf16 v[36:39], v[200:203], v[216:219], v[36:39]
	v_mfma_f32_16x16x32_bf16 v[24:27], v[192:195], v[224:227], v[24:27]
	v_mfma_f32_16x16x32_bf16 v[20:23], v[200:203], v[224:227], v[20:23]
	v_mfma_f32_16x16x32_bf16 v[8:11], v[192:195], v[232:235], v[8:11]
	v_mfma_f32_16x16x32_bf16 v[4:7], v[200:203], v[232:235], v[4:7]
	s_setprio 0
	s_barrier
	s_add_i32 s57, s57, 2
	s_add_u32 s51, s51, 0x100
	s_addc_u32 s56, s56, 0
	s_cmpk_gt_u32 s57, 0x55
	s_mov_b64 s[14:15], s[16:17]
	s_cbranch_scc0 .LBB0_167
	s_and_b64 vcc, exec, s[10:11]
	s_cbranch_vccz .LBB0_170
	s_barrier

; #define PG8_STAGE(bufoff, gbase, voff) do { _Pragma("unroll") for (int _i = 0; _i < 2; ++_i) \
;         __builtin_amdgcn_global_load_lds((const unsigned*)((const char*)(gbase) + (voff)[_i]), (PG8_LAS unsigned*)(lds + (bufoff) + ldsw + _i * 8192), 16, 0, 0); } while (0)
; #define PG8_LDA(dst, b, h) do { _Pragma("unroll") for (int m = 0; m < 4; ++m) _Pragma("unroll") for (int k = 0; k < 2; ++k) dst[m][k] = *(const PG8_LAS bf16x8*)(lds + PG8_SA(b, h) + aoff + m * 2048 + k * 1024); } while (0)
; #define PG8_LDB(dst, b, h) do { _Pragma("unroll") for (int n = 0; n < 2; ++n) _Pragma("unroll") for (int k = 0; k < 2; ++k) dst[n][k] = *(const PG8_LAS bf16x8*)(lds + PG8_SB(b, h) + boff + n * 2048 + k * 1024); } while (0)
; #define PG8_MMA(ai, bj, At, Bt) do { __builtin_amdgcn_s_setprio(1); _Pragma("unroll") for (int m = 0; m < 4; ++m) _Pragma("unroll") for (int n = 0; n < 2; ++n) _Pragma("unroll") for (int k = 0; k < 2; ++k) \
;         acc[ai][bj][m][n] = __builtin_amdgcn_mfma_f32_16x16x32_bf16(Bt[n][k], At[m][k], acc[ai][bj][m][n], 0, 0, 0); __builtin_amdgcn_s_setprio(0); } while (0)
; #define PG8_WAIT_V(n) asm volatile("s_waitcnt vmcnt(" #n ")" ::: "memory")
; #define PG8_WAIT_L(n) asm volatile("s_waitcnt lgkmcnt(" #n ")" ::: "memory")
; template <class Epi, class Sched, bool ALIGN_EPI = false, bool SP2 = false>
; __device__ __forceinline__ void gemm_phase(PG8_LAS unsigned char* lds, const Gemm g, const Sched& S, const Epi& E) {
;     ...
;             const bool last = (t == nt - 2);
;             const char* a1 = cA + (size_t)(t + 1) * kstep;
;             const char* a2 = last ? nA : cA + (size_t)(t + 2) * kstep; const char* b2 = last ? nB : cB + (size_t)(t + 2) * kstep;
;             const char* a3 = a2 + kstep; const char* b3 = b2 + kstep;
;             if (last && has_next) S.a_ready(nxt);
;             if constexpr (SP2) {
;             PG8_LDB(B0, 0, 0); PG8_LDB(B1, 0, 1); PG8_SCHED; PG8_LDA(At, 0, 0); PG8_STAGE(PG8_SA(1, 1), a1 + hstep, voffA);
;             PG8_WAIT_V(8); PG8_WAIT_L(0); PG8_BAR; PG8_MMA(0, 0, At, B0); PG8_MMA(0, 1, At, B1); PG8_BAR; PG8_SCHED;
;             PG8_LDA(At, 0, 1); PG8_STAGE(PG8_SB(0, 0), b2, voffB); PG8_STAGE(PG8_SB(0, 1), b2 + hstep, voffB); PG8_STAGE(PG8_SA(0, 0), a2, voffA);
;             PG8_WAIT_V(8); PG8_WAIT_L(0); PG8_BAR; PG8_MMA(1, 0, At, B0); PG8_MMA(1, 1, At, B1); PG8_BAR; PG8_SCHED;
.LBB0_251:
	s_add_u32 s20, s18, 0xfff80080
	s_addc_u32 s21, s19, -1
	s_add_i32 s63, 0, 0x10000
	s_cmp_eq_u32 s57, 28
	s_cselect_b32 s23, s11, s21
	s_cselect_b32 s22, s45, s20
	v_add_u32_e32 v151, s63, v156
	s_cselect_b32 s21, s7, s56
	s_cselect_b32 s20, s50, s51
	s_add_i32 s66, 0, 0x14000
	ds_read_b128 v[184:187], v151
	ds_read_b128 v[188:191], v151 offset:1024
	ds_read_b128 v[192:195], v151 offset:2048
	ds_read_b128 v[196:199], v151 offset:3072
	v_add_u32_e32 v151, s66, v156
	ds_read_b128 v[200:203], v151
	ds_read_b128 v[204:207], v151 offset:1024
	ds_read_b128 v[208:211], v151 offset:2048
	ds_read_b128 v[212:215], v151 offset:3072
	s_add_i32 m0, s17, 0xc000
	ds_read_b128 v[216:219], v160
	ds_read_b128 v[220:223], v160 offset:1024
	ds_read_b128 v[224:227], v160 offset:2048
	ds_read_b128 v[228:231], v160 offset:3072
	ds_read_b128 v[232:235], v160 offset:4096
	ds_read_b128 v[236:239], v160 offset:5120
	ds_read_b128 v[240:243], v160 offset:6144
	ds_read_b128 v[244:247], v160 offset:7168
	global_load_lds_dwordx4 v136, s[18:19]
	s_add_i32 m0, s17, 0xe000
	s_nop 0
	global_load_lds_dwordx4 v138, s[18:19]
	s_waitcnt vmcnt(8)
	s_waitcnt lgkmcnt(0)
	s_barrier
	s_setprio 1
	s_waitcnt lgkmcnt(0)
	v_mfma_f32_16x16x32_bf16 v[128:131], v[184:187], v[216:219], v[128:131]
	v_mfma_f32_16x16x32_bf16 v[124:127], v[192:195], v[216:219], v[124:127]
	v_mfma_f32_16x16x32_bf16 v[112:115], v[184:187], v[224:227], v[112:115]
	v_mfma_f32_16x16x32_bf16 v[108:111], v[192:195], v[224:227], v[108:111]
	v_mfma_f32_16x16x32_bf16 v[96:99], v[184:187], v[232:235], v[96:99]
	v_mfma_f32_16x16x32_bf16 v[92:95], v[192:195], v[232:235], v[92:95]
	v_mfma_f32_16x16x32_bf16 v[80:83], v[184:187], v[240:243], v[80:83]
	v_mfma_f32_16x16x32_bf16 v[76:79], v[192:195], v[240:243], v[76:79]
	v_mfma_f32_16x16x32_bf16 v[128:131], v[188:191], v[220:223], v[128:131]
	v_mfma_f32_16x16x32_bf16 v[124:127], v[196:199], v[220:223], v[124:127]
	v_mfma_f32_16x16x32_bf16 v[112:115], v[188:191], v[228:231], v[112:115]
	v_mfma_f32_16x16x32_bf16 v[108:111], v[196:199], v[228:231], v[108:111]
	v_mfma_f32_16x16x32_bf16 v[96:99], v[188:191], v[236:239], v[96:99]
	v_mfma_f32_16x16x32_bf16 v[92:95], v[196:199], v[236:239], v[92:95]
	v_mfma_f32_16x16x32_bf16 v[80:83], v[188:191], v[244:247], v[80:83]
	v_mfma_f32_16x16x32_bf16 v[76:79], v[196:199], v[244:247], v[76:79]
	s_setprio 0
	s_setprio 1
	v_mfma_f32_16x16x32_bf16 v[120:123], v[200:203], v[216:219], v[120:123]
	v_mfma_f32_16x16x32_bf16 v[116:119], v[208:211], v[216:219], v[116:119]
	v_mfma_f32_16x16x32_bf16 v[104:107], v[200:203], v[224:227], v[104:107]
	v_mfma_f32_16x16x32_bf16 v[100:103], v[208:211], v[224:227], v[100:103]
	v_mfma_f32_16x16x32_bf16 v[88:91], v[200:203], v[232:235], v[88:91]
	v_mfma_f32_16x16x32_bf16 v[84:87], v[208:211], v[232:235], v[84:87]
	v_mfma_f32_16x16x32_bf16 v[72:75], v[200:203], v[240:243], v[72:75]
	v_mfma_f32_16x16x32_bf16 v[68:71], v[208:211], v[240:243], v[68:71]
	v_mfma_f32_16x16x32_bf16 v[120:123], v[204:207], v[220:223], v[120:123]
	v_mfma_f32_16x16x32_bf16 v[116:119], v[212:215], v[220:223], v[116:119]
	v_mfma_f32_16x16x32_bf16 v[104:107], v[204:207], v[228:231], v[104:107]
	v_mfma_f32_16x16x32_bf16 v[100:103], v[212:215], v[228:231], v[100:103]
	v_mfma_f32_16x16x32_bf16 v[88:91], v[204:207], v[236:239], v[88:91]
	v_mfma_f32_16x16x32_bf16 v[84:87], v[212:215], v[236:239], v[84:87]
	v_mfma_f32_16x16x32_bf16 v[72:75], v[204:207], v[244:247], v[72:75]
	v_mfma_f32_16x16x32_bf16 v[68:71], v[212:215], v[244:247], v[68:71]
	s_setprio 0
	s_barrier
	s_add_i32 s63, s63, s27
	v_lshl_add_u64 v[152:153], s[20:21], 0, v[2:3]
	s_mov_b32 m0, s63
	ds_read_b128 v[216:219], v160 offset:16384
	ds_read_b128 v[220:223], v160 offset:17408
	ds_read_b128 v[224:227], v160 offset:18432
	ds_read_b128 v[228:231], v160 offset:19456
	ds_read_b128 v[232:235], v160 offset:20480
	ds_read_b128 v[236:239], v160 offset:21504
	ds_read_b128 v[240:243], v160 offset:22528
	ds_read_b128 v[244:247], v160 offset:23552
	global_load_lds_dwordx4 v[152:153], off
	s_add_i32 m0, s63, 0x2000
	s_add_u32 s64, s20, 0x80000
	v_lshl_add_u64 v[166:167], s[20:21], 0, v[0:1]
	s_addc_u32 s65, s21, 0
	s_add_i32 s63, s66, s27
	global_load_lds_dwordx4 v[166:167], off
	s_mov_b32 m0, s63
	v_lshl_add_u64 v[250:251], s[22:23], 0, v[132:133]
	global_load_lds_dwordx4 v2, s[64:65]
	s_add_i32 m0, s63, 0x2000
	s_nop 0
	global_load_lds_dwordx4 v0, s[64:65]
	v_lshl_add_u64 v[248:249], s[22:23], 0, v[134:135]
	s_mov_b32 m0, s17
	s_nop 0
	global_load_lds_dwordx4 v[248:249], off
	s_mov_b32 m0, s29
	s_nop 0
	global_load_lds_dwordx4 v[250:251], off
	s_waitcnt vmcnt(8)
	s_waitcnt lgkmcnt(0)
	s_barrier
; #define PG8_STAGE(bufoff, gbase, voff) do { _Pragma("unroll") for (int _i = 0; _i < 2; ++_i) \
;         __builtin_amdgcn_global_load_lds((const unsigned*)((const char*)(gbase) + (voff)[_i]), (PG8_LAS unsigned*)(lds + (bufoff) + ldsw + _i * 8192), 16, 0, 0); } while (0)
; #define PG8_LDA(dst, b, h) do { _Pragma("unroll") for (int m = 0; m < 4; ++m) _Pragma("unroll") for (int k = 0; k < 2; ++k) dst[m][k] = *(const PG8_LAS bf16x8*)(lds + PG8_SA(b, h) + aoff + m * 2048 + k * 1024); } while (0)
; #define PG8_LDB(dst, b, h) do { _Pragma("unroll") for (int n = 0; n < 2; ++n) _Pragma("unroll") for (int k = 0; k < 2; ++k) dst[n][k] = *(const PG8_LAS bf16x8*)(lds + PG8_SB(b, h) + boff + n * 2048 + k * 1024); } while (0)
; #define PG8_MMA(ai, bj, At, Bt) do { __builtin_amdgcn_s_setprio(1); _Pragma("unroll") for (int m = 0; m < 4; ++m) _Pragma("unroll") for (int n = 0; n < 2; ++n) _Pragma("unroll") for (int k = 0; k < 2; ++k) \
;         acc[ai][bj][m][n] = __builtin_amdgcn_mfma_f32_16x16x32_bf16(Bt[n][k], At[m][k], acc[ai][bj][m][n], 0, 0, 0); __builtin_amdgcn_s_setprio(0); } while (0)
; #define PG8_WAIT_V(n) asm volatile("s_waitcnt vmcnt(" #n ")" ::: "memory")
; #define PG8_WAIT_L(n) asm volatile("s_waitcnt lgkmcnt(" #n ")" ::: "memory")
; #define PG8_BAR __builtin_amdgcn_s_barrier()
; #define PG8_SCHED __builtin_amdgcn_sched_barrier(0)
; template <class Epi, class Sched, bool ALIGN_EPI = false, bool SP2 = false>
; __device__ __forceinline__ void gemm_phase(PG8_LAS unsigned char* lds, const Gemm g, const Sched& S, const Epi& E) {
;     ...
;             PG8_WAIT_V(8); PG8_WAIT_L(0); PG8_BAR; PG8_MMA(1, 0, At, B0); PG8_MMA(1, 1, At, B1); PG8_BAR; PG8_SCHED;
;             PG8_LDB(B0, 1, 0); PG8_LDB(B1, 1, 1); PG8_SCHED; PG8_LDA(At, 1, 0); PG8_STAGE(PG8_SA(0, 1), a2 + hstep, voffA);
;             PG8_WAIT_V(8); PG8_WAIT_L(0); PG8_BAR; PG8_MMA(0, 0, At, B0); PG8_MMA(0, 1, At, B1); PG8_BAR; PG8_SCHED;
	s_setprio 1
	s_waitcnt lgkmcnt(0)
	v_mfma_f32_16x16x32_bf16 v[64:67], v[184:187], v[216:219], v[64:67]
	v_mfma_f32_16x16x32_bf16 v[60:63], v[192:195], v[216:219], v[60:63]
	v_mfma_f32_16x16x32_bf16 v[48:51], v[184:187], v[224:227], v[48:51]
	v_mfma_f32_16x16x32_bf16 v[44:47], v[192:195], v[224:227], v[44:47]
	v_mfma_f32_16x16x32_bf16 v[32:35], v[184:187], v[232:235], v[32:35]
	v_mfma_f32_16x16x32_bf16 v[28:31], v[192:195], v[232:235], v[28:31]
	v_mfma_f32_16x16x32_bf16 v[16:19], v[184:187], v[240:243], v[16:19]
	v_mfma_f32_16x16x32_bf16 v[12:15], v[192:195], v[240:243], v[12:15]
	v_mfma_f32_16x16x32_bf16 v[64:67], v[188:191], v[220:223], v[64:67]
	v_mfma_f32_16x16x32_bf16 v[60:63], v[196:199], v[220:223], v[60:63]
	v_mfma_f32_16x16x32_bf16 v[48:51], v[188:191], v[228:231], v[48:51]
	v_mfma_f32_16x16x32_bf16 v[44:47], v[196:199], v[228:231], v[44:47]
	v_mfma_f32_16x16x32_bf16 v[32:35], v[188:191], v[236:239], v[32:35]
	v_mfma_f32_16x16x32_bf16 v[28:31], v[196:199], v[236:239], v[28:31]
	v_mfma_f32_16x16x32_bf16 v[16:19], v[188:191], v[244:247], v[16:19]
	v_mfma_f32_16x16x32_bf16 v[12:15], v[196:199], v[244:247], v[12:15]
	s_setprio 0
	s_setprio 1
	v_mfma_f32_16x16x32_bf16 v[56:59], v[200:203], v[216:219], v[56:59]
	v_mfma_f32_16x16x32_bf16 v[52:55], v[208:211], v[216:219], v[52:55]
	v_mfma_f32_16x16x32_bf16 v[40:43], v[200:203], v[224:227], v[40:43]
	v_mfma_f32_16x16x32_bf16 v[36:39], v[208:211], v[224:227], v[36:39]
	v_mfma_f32_16x16x32_bf16 v[24:27], v[200:203], v[232:235], v[24:27]
	v_mfma_f32_16x16x32_bf16 v[20:23], v[208:211], v[232:235], v[20:23]
	v_mfma_f32_16x16x32_bf16 v[8:11], v[200:203], v[240:243], v[8:11]
	v_mfma_f32_16x16x32_bf16 v[4:7], v[208:211], v[240:243], v[4:7]
	v_mfma_f32_16x16x32_bf16 v[56:59], v[204:207], v[220:223], v[56:59]
	v_mfma_f32_16x16x32_bf16 v[52:55], v[212:215], v[220:223], v[52:55]
	v_mfma_f32_16x16x32_bf16 v[40:43], v[204:207], v[228:231], v[40:43]
	v_mfma_f32_16x16x32_bf16 v[36:39], v[212:215], v[228:231], v[36:39]
	v_mfma_f32_16x16x32_bf16 v[24:27], v[204:207], v[236:239], v[24:27]
	v_mfma_f32_16x16x32_bf16 v[20:23], v[212:215], v[236:239], v[20:23]
	v_mfma_f32_16x16x32_bf16 v[8:11], v[204:207], v[244:247], v[8:11]
	v_mfma_f32_16x16x32_bf16 v[4:7], v[212:215], v[244:247], v[4:7]
	s_setprio 0
	s_barrier
	s_add_i32 s63, 0, 0x18000
	v_add_u32_e32 v151, s63, v156
	s_add_i32 s64, 0, 0x1c000
	ds_read_b128 v[184:187], v151
	ds_read_b128 v[188:191], v151 offset:1024
	ds_read_b128 v[192:195], v151 offset:2048
	ds_read_b128 v[196:199], v151 offset:3072
	v_add_u32_e32 v151, s64, v156
	ds_read_b128 v[200:203], v151
	ds_read_b128 v[204:207], v151 offset:1024
	ds_read_b128 v[208:211], v151 offset:2048
	ds_read_b128 v[212:215], v151 offset:3072
	s_add_u32 s22, s22, 0x80000
	s_addc_u32 s23, s23, 0
	s_mov_b32 m0, s30
	ds_read_b128 v[216:219], v160 offset:32768
	ds_read_b128 v[220:223], v160 offset:33792
	ds_read_b128 v[224:227], v160 offset:34816
	ds_read_b128 v[228:231], v160 offset:35840
	ds_read_b128 v[232:235], v160 offset:36864
	ds_read_b128 v[236:239], v160 offset:37888
	ds_read_b128 v[240:243], v160 offset:38912
	ds_read_b128 v[244:247], v160 offset:39936
	global_load_lds_dwordx4 v134, s[22:23]
	s_mov_b32 m0, s31
	s_nop 0
	global_load_lds_dwordx4 v132, s[22:23]
	s_waitcnt vmcnt(8)
	s_waitcnt lgkmcnt(0)
	s_barrier
	s_setprio 1
	s_waitcnt lgkmcnt(0)
	v_mfma_f32_16x16x32_bf16 v[128:131], v[184:187], v[216:219], v[128:131]
	v_mfma_f32_16x16x32_bf16 v[124:127], v[192:195], v[216:219], v[124:127]
	v_mfma_f32_16x16x32_bf16 v[112:115], v[184:187], v[224:227], v[112:115]
	v_mfma_f32_16x16x32_bf16 v[108:111], v[192:195], v[224:227], v[108:111]
	v_mfma_f32_16x16x32_bf16 v[96:99], v[184:187], v[232:235], v[96:99]
	v_mfma_f32_16x16x32_bf16 v[92:95], v[192:195], v[232:235], v[92:95]
	v_mfma_f32_16x16x32_bf16 v[80:83], v[184:187], v[240:243], v[80:83]
	v_mfma_f32_16x16x32_bf16 v[76:79], v[192:195], v[240:243], v[76:79]
	v_mfma_f32_16x16x32_bf16 v[128:131], v[188:191], v[220:223], v[128:131]
	v_mfma_f32_16x16x32_bf16 v[124:127], v[196:199], v[220:223], v[124:127]
	v_mfma_f32_16x16x32_bf16 v[112:115], v[188:191], v[228:231], v[112:115]
	v_mfma_f32_16x16x32_bf16 v[108:111], v[196:199], v[228:231], v[108:111]
	v_mfma_f32_16x16x32_bf16 v[96:99], v[188:191], v[236:239], v[96:99]
	v_mfma_f32_16x16x32_bf16 v[92:95], v[196:199], v[236:239], v[92:95]
	v_mfma_f32_16x16x32_bf16 v[80:83], v[188:191], v[244:247], v[80:83]
	v_mfma_f32_16x16x32_bf16 v[76:79], v[196:199], v[244:247], v[76:79]
	s_setprio 0
	s_setprio 1
	v_mfma_f32_16x16x32_bf16 v[120:123], v[200:203], v[216:219], v[120:123]
	v_mfma_f32_16x16x32_bf16 v[116:119], v[208:211], v[216:219], v[116:119]
	v_mfma_f32_16x16x32_bf16 v[104:107], v[200:203], v[224:227], v[104:107]
	v_mfma_f32_16x16x32_bf16 v[100:103], v[208:211], v[224:227], v[100:103]
	v_mfma_f32_16x16x32_bf16 v[88:91], v[200:203], v[232:235], v[88:91]
	v_mfma_f32_16x16x32_bf16 v[84:87], v[208:211], v[232:235], v[84:87]
	v_mfma_f32_16x16x32_bf16 v[72:75], v[200:203], v[240:243], v[72:75]
	v_mfma_f32_16x16x32_bf16 v[68:71], v[208:211], v[240:243], v[68:71]
	v_mfma_f32_16x16x32_bf16 v[120:123], v[204:207], v[220:223], v[120:123]
	v_mfma_f32_16x16x32_bf16 v[116:119], v[212:215], v[220:223], v[116:119]
	v_mfma_f32_16x16x32_bf16 v[104:107], v[204:207], v[228:231], v[104:107]
	v_mfma_f32_16x16x32_bf16 v[100:103], v[212:215], v[228:231], v[100:103]
	v_mfma_f32_16x16x32_bf16 v[88:91], v[204:207], v[236:239], v[88:91]
	v_mfma_f32_16x16x32_bf16 v[84:87], v[212:215], v[236:239], v[84:87]
	v_mfma_f32_16x16x32_bf16 v[72:75], v[204:207], v[244:247], v[72:75]
	v_mfma_f32_16x16x32_bf16 v[68:71], v[212:215], v[244:247], v[68:71]
	s_setprio 0
	s_barrier
; #define PG8_STAGE(bufoff, gbase, voff) do { _Pragma("unroll") for (int _i = 0; _i < 2; ++_i) \
;         __builtin_amdgcn_global_load_lds((const unsigned*)((const char*)(gbase) + (voff)[_i]), (PG8_LAS unsigned*)(lds + (bufoff) + ldsw + _i * 8192), 16, 0, 0); } while (0)
; #define PG8_LDA(dst, b, h) do { _Pragma("unroll") for (int m = 0; m < 4; ++m) _Pragma("unroll") for (int k = 0; k < 2; ++k) dst[m][k] = *(const PG8_LAS bf16x8*)(lds + PG8_SA(b, h) + aoff + m * 2048 + k * 1024); } while (0)
; #define PG8_MMA(ai, bj, At, Bt) do { __builtin_amdgcn_s_setprio(1); _Pragma("unroll") for (int m = 0; m < 4; ++m) _Pragma("unroll") for (int n = 0; n < 2; ++n) _Pragma("unroll") for (int k = 0; k < 2; ++k) \
;         acc[ai][bj][m][n] = __builtin_amdgcn_mfma_f32_16x16x32_bf16(Bt[n][k], At[m][k], acc[ai][bj][m][n], 0, 0, 0); __builtin_amdgcn_s_setprio(0); } while (0)
; #define PG8_WAIT_V(n) asm volatile("s_waitcnt vmcnt(" #n ")" ::: "memory")
; #define PG8_WAIT_L(n) asm volatile("s_waitcnt lgkmcnt(" #n ")" ::: "memory")
; #define PG8_BAR __builtin_amdgcn_s_barrier()
; #define PG8_SCHED __builtin_amdgcn_sched_barrier(0)
; template <class Epi, class Sched, bool ALIGN_EPI = false, bool SP2 = false>
; __device__ __forceinline__ void gemm_phase(PG8_LAS unsigned char* lds, const Gemm g, const Sched& S, const Epi& E) {
;     ...
;             PG8_LDA(At, 1, 1); PG8_STAGE(PG8_SB(1, 0), b3, voffB); PG8_STAGE(PG8_SB(1, 1), b3 + hstep, voffB); PG8_STAGE(PG8_SA(1, 0), a3, voffA);
;             PG8_WAIT_V(8); PG8_WAIT_L(0); PG8_BAR; PG8_MMA(1, 0, At, B0); PG8_MMA(1, 1, At, B1); PG8_BAR; PG8_SCHED;
;     ...
;         if constexpr (ALIGN_EPI) { if (wr == 0) PG8_BAR; }
	s_add_i32 s22, s63, s27
	v_lshl_add_u64 v[152:153], v[152:153], 0, s[36:37]
	s_mov_b32 m0, s22
	ds_read_b128 v[216:219], v160 offset:49152
	ds_read_b128 v[220:223], v160 offset:50176
	ds_read_b128 v[224:227], v160 offset:51200
	ds_read_b128 v[228:231], v160 offset:52224
	ds_read_b128 v[232:235], v160 offset:53248
	ds_read_b128 v[236:239], v160 offset:54272
	ds_read_b128 v[240:243], v160 offset:55296
	ds_read_b128 v[244:247], v160 offset:56320
	global_load_lds_dwordx4 v[152:153], off
	s_add_i32 m0, s22, 0x2000
	s_add_u32 s20, s20, 0x80080
	v_lshl_add_u64 v[152:153], v[166:167], 0, s[36:37]
	s_addc_u32 s21, s21, 0
	s_add_i32 s22, s64, s27
	global_load_lds_dwordx4 v[152:153], off
	s_mov_b32 m0, s22
	s_nop 0
	global_load_lds_dwordx4 v2, s[20:21]
	s_add_i32 m0, s22, 0x2000
	s_nop 0
	global_load_lds_dwordx4 v0, s[20:21]
	v_lshl_add_u64 v[152:153], v[248:249], 0, s[36:37]
	s_mov_b32 m0, s34
	s_nop 0
	global_load_lds_dwordx4 v[152:153], off
	v_lshl_add_u64 v[152:153], v[250:251], 0, s[36:37]
	s_mov_b32 m0, s35
	s_nop 0
	global_load_lds_dwordx4 v[152:153], off
	s_waitcnt vmcnt(8)
	s_waitcnt lgkmcnt(0)
	s_barrier
	s_setprio 1
	s_waitcnt lgkmcnt(0)
	v_mfma_f32_16x16x32_bf16 v[64:67], v[184:187], v[216:219], v[64:67]
	v_mfma_f32_16x16x32_bf16 v[60:63], v[192:195], v[216:219], v[60:63]
	v_mfma_f32_16x16x32_bf16 v[48:51], v[184:187], v[224:227], v[48:51]
	v_mfma_f32_16x16x32_bf16 v[44:47], v[192:195], v[224:227], v[44:47]
	v_mfma_f32_16x16x32_bf16 v[32:35], v[184:187], v[232:235], v[32:35]
	v_mfma_f32_16x16x32_bf16 v[28:31], v[192:195], v[232:235], v[28:31]
	v_mfma_f32_16x16x32_bf16 v[16:19], v[184:187], v[240:243], v[16:19]
	v_mfma_f32_16x16x32_bf16 v[12:15], v[192:195], v[240:243], v[12:15]
	v_mfma_f32_16x16x32_bf16 v[64:67], v[188:191], v[220:223], v[64:67]
	v_mfma_f32_16x16x32_bf16 v[60:63], v[196:199], v[220:223], v[60:63]
	v_mfma_f32_16x16x32_bf16 v[48:51], v[188:191], v[228:231], v[48:51]
	v_mfma_f32_16x16x32_bf16 v[44:47], v[196:199], v[228:231], v[44:47]
	v_mfma_f32_16x16x32_bf16 v[32:35], v[188:191], v[236:239], v[32:35]
	v_mfma_f32_16x16x32_bf16 v[28:31], v[196:199], v[236:239], v[28:31]
	v_mfma_f32_16x16x32_bf16 v[16:19], v[188:191], v[244:247], v[16:19]
	v_mfma_f32_16x16x32_bf16 v[12:15], v[196:199], v[244:247], v[12:15]
	s_setprio 0
	s_setprio 1
	v_mfma_f32_16x16x32_bf16 v[56:59], v[200:203], v[216:219], v[56:59]
	v_mfma_f32_16x16x32_bf16 v[52:55], v[208:211], v[216:219], v[52:55]
	v_mfma_f32_16x16x32_bf16 v[40:43], v[200:203], v[224:227], v[40:43]
	v_mfma_f32_16x16x32_bf16 v[36:39], v[208:211], v[224:227], v[36:39]
	v_mfma_f32_16x16x32_bf16 v[24:27], v[200:203], v[232:235], v[24:27]
	v_mfma_f32_16x16x32_bf16 v[20:23], v[208:211], v[232:235], v[20:23]
	v_mfma_f32_16x16x32_bf16 v[8:11], v[200:203], v[240:243], v[8:11]
	v_mfma_f32_16x16x32_bf16 v[4:7], v[208:211], v[240:243], v[4:7]
	v_mfma_f32_16x16x32_bf16 v[56:59], v[204:207], v[220:223], v[56:59]
	v_mfma_f32_16x16x32_bf16 v[52:55], v[212:215], v[220:223], v[52:55]
	v_mfma_f32_16x16x32_bf16 v[40:43], v[204:207], v[228:231], v[40:43]
	v_mfma_f32_16x16x32_bf16 v[36:39], v[212:215], v[228:231], v[36:39]
	v_mfma_f32_16x16x32_bf16 v[24:27], v[204:207], v[236:239], v[24:27]
	v_mfma_f32_16x16x32_bf16 v[20:23], v[212:215], v[236:239], v[20:23]
	v_mfma_f32_16x16x32_bf16 v[8:11], v[204:207], v[244:247], v[8:11]
	v_mfma_f32_16x16x32_bf16 v[4:7], v[212:215], v[244:247], v[4:7]
	s_setprio 0
	s_barrier
	s_add_i32 s57, s57, 2
	s_add_u32 s18, s18, 0x100
	s_addc_u32 s19, s19, 0
	s_add_u32 s51, s51, 0x100
	s_addc_u32 s56, s56, 0
	s_cmp_gt_u32 s57, 29
	s_cbranch_scc0 .LBB0_251
	s_and_b64 vcc, exec, s[4:5]
	s_cbranch_vccz .LBB0_254
	s_barrier

; #define PG8_STAGE(bufoff, gbase, voff) do { _Pragma("unroll") for (int _i = 0; _i < 2; ++_i) \
;         __builtin_amdgcn_global_load_lds((const unsigned*)((const char*)(gbase) + (voff)[_i]), (PG8_LAS unsigned*)(lds + (bufoff) + ldsw + _i * 8192), 16, 0, 0); } while (0)
; #define PG8_LDA(dst, b, h) do { _Pragma("unroll") for (int m = 0; m < 4; ++m) _Pragma("unroll") for (int k = 0; k < 2; ++k) dst[m][k] = *(const PG8_LAS bf16x8*)(lds + PG8_SA(b, h) + aoff + m * 2048 + k * 1024); } while (0)
; #define PG8_LDB(dst, b, h) do { _Pragma("unroll") for (int n = 0; n < 2; ++n) _Pragma("unroll") for (int k = 0; k < 2; ++k) dst[n][k] = *(const PG8_LAS bf16x8*)(lds + PG8_SB(b, h) + boff + n * 2048 + k * 1024); } while (0)
; #define PG8_MMA(ai, bj, At, Bt) do { __builtin_amdgcn_s_setprio(1); _Pragma("unroll") for (int m = 0; m < 4; ++m) _Pragma("unroll") for (int n = 0; n < 2; ++n) _Pragma("unroll") for (int k = 0; k < 2; ++k) \
;         acc[ai][bj][m][n] = __builtin_amdgcn_mfma_f32_16x16x32_bf16(Bt[n][k], At[m][k], acc[ai][bj][m][n], 0, 0, 0); __builtin_amdgcn_s_setprio(0); } while (0)
; #define PG8_WAIT_V(n) asm volatile("s_waitcnt vmcnt(" #n ")" ::: "memory")
; #define PG8_WAIT_L(n) asm volatile("s_waitcnt lgkmcnt(" #n ")" ::: "memory")
; template <class Epi, class Sched, bool ALIGN_EPI = false, bool SP2 = false>
; __device__ __forceinline__ void gemm_phase(PG8_LAS unsigned char* lds, const Gemm g, const Sched& S, const Epi& E) {
;     ...
;             const bool last = (t == nt - 2);
;             const char* a1 = cA + (size_t)(t + 1) * kstep;
;             const char* a2 = last ? nA : cA + (size_t)(t + 2) * kstep; const char* b2 = last ? nB : cB + (size_t)(t + 2) * kstep;
;             const char* a3 = a2 + kstep; const char* b3 = b2 + kstep;
;             if (last && has_next) S.a_ready(nxt);
;             if constexpr (SP2) {
;             PG8_LDB(B0, 0, 0); PG8_LDB(B1, 0, 1); PG8_SCHED; PG8_LDA(At, 0, 0); PG8_STAGE(PG8_SA(1, 1), a1 + hstep, voffA);
;             PG8_WAIT_V(8); PG8_WAIT_L(0); PG8_BAR; PG8_MMA(0, 0, At, B0); PG8_MMA(0, 1, At, B1); PG8_BAR; PG8_SCHED;
;             PG8_LDA(At, 0, 1); PG8_STAGE(PG8_SB(0, 0), b2, voffB); PG8_STAGE(PG8_SB(0, 1), b2 + hstep, voffB); PG8_STAGE(PG8_SA(0, 0), a2, voffA);
;             PG8_WAIT_V(8); PG8_WAIT_L(0); PG8_BAR; PG8_MMA(1, 0, At, B0); PG8_MMA(1, 1, At, B1); PG8_BAR; PG8_SCHED;
.LBB0_483:
	s_add_u32 s24, s22, 0xfff80080
	s_addc_u32 s25, s23, -1
	s_add_i32 s65, 0, 0x10000
	s_cmp_eq_u32 s64, 28
	s_cselect_b32 s27, s13, s25
	s_cselect_b32 s26, s19, s24
	s_cselect_b32 s25, s11, s63
	s_cselect_b32 s24, s56, s57
	s_add_i32 s76, 0, 0x14000
	v_add_u32_e32 v162, s65, v185
	v_add_u32_e32 v166, s76, v185
	ds_read_b128 v[132:135], v162
	ds_read_b128 v[136:139], v162 offset:1024
	ds_read_b128 v[158:161], v162 offset:2048
	ds_read_b128 v[162:165], v162 offset:3072
	ds_read_b128 v[188:191], v166
	ds_read_b128 v[192:195], v166 offset:1024
	ds_read_b128 v[196:199], v166 offset:2048
	ds_read_b128 v[200:203], v166 offset:3072
	s_add_i32 m0, s21, 0xc000
	ds_read_b128 v[204:207], v187
	ds_read_b128 v[208:211], v187 offset:1024
	ds_read_b128 v[212:215], v187 offset:2048
	ds_read_b128 v[216:219], v187 offset:3072
	ds_read_b128 v[220:223], v187 offset:4096
	ds_read_b128 v[224:227], v187 offset:5120
	ds_read_b128 v[228:231], v187 offset:6144
	ds_read_b128 v[232:235], v187 offset:7168
	global_load_lds_dwordx4 v154, s[22:23]
	s_add_i32 m0, s21, 0xe000
	s_nop 0
	global_load_lds_dwordx4 v156, s[22:23]
	s_waitcnt vmcnt(8)
	s_waitcnt lgkmcnt(0)
	s_barrier
	s_setprio 1
	s_waitcnt lgkmcnt(0)
	v_mfma_f32_16x16x32_bf16 v[128:131], v[132:135], v[204:207], v[128:131]
	v_mfma_f32_16x16x32_bf16 v[124:127], v[158:161], v[204:207], v[124:127]
	v_mfma_f32_16x16x32_bf16 v[112:115], v[132:135], v[212:215], v[112:115]
	v_mfma_f32_16x16x32_bf16 v[108:111], v[158:161], v[212:215], v[108:111]
	v_mfma_f32_16x16x32_bf16 v[96:99], v[132:135], v[220:223], v[96:99]
	v_mfma_f32_16x16x32_bf16 v[92:95], v[158:161], v[220:223], v[92:95]
	v_mfma_f32_16x16x32_bf16 v[80:83], v[132:135], v[228:231], v[80:83]
	v_mfma_f32_16x16x32_bf16 v[76:79], v[158:161], v[228:231], v[76:79]
	v_mfma_f32_16x16x32_bf16 v[128:131], v[136:139], v[208:211], v[128:131]
	v_mfma_f32_16x16x32_bf16 v[124:127], v[162:165], v[208:211], v[124:127]
	v_mfma_f32_16x16x32_bf16 v[112:115], v[136:139], v[216:219], v[112:115]
	v_mfma_f32_16x16x32_bf16 v[108:111], v[162:165], v[216:219], v[108:111]
	v_mfma_f32_16x16x32_bf16 v[96:99], v[136:139], v[224:227], v[96:99]
	v_mfma_f32_16x16x32_bf16 v[92:95], v[162:165], v[224:227], v[92:95]
	v_mfma_f32_16x16x32_bf16 v[80:83], v[136:139], v[232:235], v[80:83]
	v_mfma_f32_16x16x32_bf16 v[76:79], v[162:165], v[232:235], v[76:79]
	s_setprio 0
	s_setprio 1
	v_mfma_f32_16x16x32_bf16 v[120:123], v[188:191], v[204:207], v[120:123]
	v_mfma_f32_16x16x32_bf16 v[116:119], v[196:199], v[204:207], v[116:119]
	v_mfma_f32_16x16x32_bf16 v[104:107], v[188:191], v[212:215], v[104:107]
	v_mfma_f32_16x16x32_bf16 v[100:103], v[196:199], v[212:215], v[100:103]
	v_mfma_f32_16x16x32_bf16 v[88:91], v[188:191], v[220:223], v[88:91]
	v_mfma_f32_16x16x32_bf16 v[84:87], v[196:199], v[220:223], v[84:87]
	v_mfma_f32_16x16x32_bf16 v[72:75], v[188:191], v[228:231], v[72:75]
	v_mfma_f32_16x16x32_bf16 v[68:71], v[196:199], v[228:231], v[68:71]
	v_mfma_f32_16x16x32_bf16 v[120:123], v[192:195], v[208:211], v[120:123]
	v_mfma_f32_16x16x32_bf16 v[116:119], v[200:203], v[208:211], v[116:119]
	v_mfma_f32_16x16x32_bf16 v[104:107], v[192:195], v[216:219], v[104:107]
	v_mfma_f32_16x16x32_bf16 v[100:103], v[200:203], v[216:219], v[100:103]
	v_mfma_f32_16x16x32_bf16 v[88:91], v[192:195], v[224:227], v[88:91]
	v_mfma_f32_16x16x32_bf16 v[84:87], v[200:203], v[224:227], v[84:87]
	v_mfma_f32_16x16x32_bf16 v[72:75], v[192:195], v[232:235], v[72:75]
	v_mfma_f32_16x16x32_bf16 v[68:71], v[200:203], v[232:235], v[68:71]
	s_setprio 0
	s_barrier
	s_add_i32 s65, s65, s31
	v_lshl_add_u64 v[166:167], s[24:25], 0, v[2:3]
	s_mov_b32 m0, s65
	ds_read_b128 v[204:207], v187 offset:16384
	ds_read_b128 v[208:211], v187 offset:17408
	ds_read_b128 v[212:215], v187 offset:18432
	ds_read_b128 v[216:219], v187 offset:19456
	ds_read_b128 v[220:223], v187 offset:20480
	ds_read_b128 v[224:227], v187 offset:21504
	ds_read_b128 v[228:231], v187 offset:22528
	ds_read_b128 v[232:235], v187 offset:23552
	global_load_lds_dwordx4 v[166:167], off
	s_add_i32 m0, s65, 0x2000
	s_add_u32 s66, s24, 0x80000
	v_lshl_add_u64 v[236:237], s[24:25], 0, v[152:153]
	s_addc_u32 s67, s25, 0
	s_add_i32 s65, s76, s31
	global_load_lds_dwordx4 v[236:237], off
	s_mov_b32 m0, s65
	v_lshl_add_u64 v[240:241], s[26:27], 0, v[150:151]
	global_load_lds_dwordx4 v2, s[66:67]
	s_add_i32 m0, s65, 0x2000
	s_nop 0
	global_load_lds_dwordx4 v152, s[66:67]
	v_lshl_add_u64 v[238:239], s[26:27], 0, v[0:1]
	s_mov_b32 m0, s21
	s_nop 0
	global_load_lds_dwordx4 v[238:239], off
	s_mov_b32 m0, s34
	s_nop 0
	global_load_lds_dwordx4 v[240:241], off
	s_waitcnt vmcnt(8)
	s_waitcnt lgkmcnt(0)
	s_barrier
; #define PG8_STAGE(bufoff, gbase, voff) do { _Pragma("unroll") for (int _i = 0; _i < 2; ++_i) \
;         __builtin_amdgcn_global_load_lds((const unsigned*)((const char*)(gbase) + (voff)[_i]), (PG8_LAS unsigned*)(lds + (bufoff) + ldsw + _i * 8192), 16, 0, 0); } while (0)
; #define PG8_LDA(dst, b, h) do { _Pragma("unroll") for (int m = 0; m < 4; ++m) _Pragma("unroll") for (int k = 0; k < 2; ++k) dst[m][k] = *(const PG8_LAS bf16x8*)(lds + PG8_SA(b, h) + aoff + m * 2048 + k * 1024); } while (0)
; #define PG8_LDB(dst, b, h) do { _Pragma("unroll") for (int n = 0; n < 2; ++n) _Pragma("unroll") for (int k = 0; k < 2; ++k) dst[n][k] = *(const PG8_LAS bf16x8*)(lds + PG8_SB(b, h) + boff + n * 2048 + k * 1024); } while (0)
; #define PG8_MMA(ai, bj, At, Bt) do { __builtin_amdgcn_s_setprio(1); _Pragma("unroll") for (int m = 0; m < 4; ++m) _Pragma("unroll") for (int n = 0; n < 2; ++n) _Pragma("unroll") for (int k = 0; k < 2; ++k) \
;         acc[ai][bj][m][n] = __builtin_amdgcn_mfma_f32_16x16x32_bf16(Bt[n][k], At[m][k], acc[ai][bj][m][n], 0, 0, 0); __builtin_amdgcn_s_setprio(0); } while (0)
; #define PG8_WAIT_V(n) asm volatile("s_waitcnt vmcnt(" #n ")" ::: "memory")
; #define PG8_WAIT_L(n) asm volatile("s_waitcnt lgkmcnt(" #n ")" ::: "memory")
; #define PG8_BAR __builtin_amdgcn_s_barrier()
; #define PG8_SCHED __builtin_amdgcn_sched_barrier(0)
; template <class Epi, class Sched, bool ALIGN_EPI = false, bool SP2 = false>
; __device__ __forceinline__ void gemm_phase(PG8_LAS unsigned char* lds, const Gemm g, const Sched& S, const Epi& E) {
;     ...
;             PG8_WAIT_V(8); PG8_WAIT_L(0); PG8_BAR; PG8_MMA(1, 0, At, B0); PG8_MMA(1, 1, At, B1); PG8_BAR; PG8_SCHED;
;             PG8_LDB(B0, 1, 0); PG8_LDB(B1, 1, 1); PG8_SCHED; PG8_LDA(At, 1, 0); PG8_STAGE(PG8_SA(0, 1), a2 + hstep, voffA);
;             PG8_WAIT_V(8); PG8_WAIT_L(0); PG8_BAR; PG8_MMA(0, 0, At, B0); PG8_MMA(0, 1, At, B1); PG8_BAR; PG8_SCHED;
	s_setprio 1
	s_waitcnt lgkmcnt(0)
	v_mfma_f32_16x16x32_bf16 v[64:67], v[132:135], v[204:207], v[64:67]
	v_mfma_f32_16x16x32_bf16 v[60:63], v[158:161], v[204:207], v[60:63]
	v_mfma_f32_16x16x32_bf16 v[48:51], v[132:135], v[212:215], v[48:51]
	v_mfma_f32_16x16x32_bf16 v[44:47], v[158:161], v[212:215], v[44:47]
	v_mfma_f32_16x16x32_bf16 v[32:35], v[132:135], v[220:223], v[32:35]
	v_mfma_f32_16x16x32_bf16 v[28:31], v[158:161], v[220:223], v[28:31]
	v_mfma_f32_16x16x32_bf16 v[16:19], v[132:135], v[228:231], v[16:19]
	v_mfma_f32_16x16x32_bf16 v[12:15], v[158:161], v[228:231], v[12:15]
	v_mfma_f32_16x16x32_bf16 v[64:67], v[136:139], v[208:211], v[64:67]
	v_mfma_f32_16x16x32_bf16 v[60:63], v[162:165], v[208:211], v[60:63]
	v_mfma_f32_16x16x32_bf16 v[48:51], v[136:139], v[216:219], v[48:51]
	v_mfma_f32_16x16x32_bf16 v[44:47], v[162:165], v[216:219], v[44:47]
	v_mfma_f32_16x16x32_bf16 v[32:35], v[136:139], v[224:227], v[32:35]
	v_mfma_f32_16x16x32_bf16 v[28:31], v[162:165], v[224:227], v[28:31]
	v_mfma_f32_16x16x32_bf16 v[16:19], v[136:139], v[232:235], v[16:19]
	v_mfma_f32_16x16x32_bf16 v[12:15], v[162:165], v[232:235], v[12:15]
	s_setprio 0
	s_setprio 1
	v_mfma_f32_16x16x32_bf16 v[56:59], v[188:191], v[204:207], v[56:59]
	v_mfma_f32_16x16x32_bf16 v[52:55], v[196:199], v[204:207], v[52:55]
	v_mfma_f32_16x16x32_bf16 v[40:43], v[188:191], v[212:215], v[40:43]
	v_mfma_f32_16x16x32_bf16 v[36:39], v[196:199], v[212:215], v[36:39]
	v_mfma_f32_16x16x32_bf16 v[24:27], v[188:191], v[220:223], v[24:27]
	v_mfma_f32_16x16x32_bf16 v[20:23], v[196:199], v[220:223], v[20:23]
	v_mfma_f32_16x16x32_bf16 v[8:11], v[188:191], v[228:231], v[8:11]
	v_mfma_f32_16x16x32_bf16 v[4:7], v[196:199], v[228:231], v[4:7]
	v_mfma_f32_16x16x32_bf16 v[56:59], v[192:195], v[208:211], v[56:59]
	v_mfma_f32_16x16x32_bf16 v[52:55], v[200:203], v[208:211], v[52:55]
	v_mfma_f32_16x16x32_bf16 v[40:43], v[192:195], v[216:219], v[40:43]
	v_mfma_f32_16x16x32_bf16 v[36:39], v[200:203], v[216:219], v[36:39]
	v_mfma_f32_16x16x32_bf16 v[24:27], v[192:195], v[224:227], v[24:27]
	v_mfma_f32_16x16x32_bf16 v[20:23], v[200:203], v[224:227], v[20:23]
	v_mfma_f32_16x16x32_bf16 v[8:11], v[192:195], v[232:235], v[8:11]
	v_mfma_f32_16x16x32_bf16 v[4:7], v[200:203], v[232:235], v[4:7]
	s_setprio 0
	s_barrier
	s_add_i32 s65, 0, 0x18000
	s_add_i32 s66, 0, 0x1c000
	v_add_u32_e32 v162, s65, v185
	v_add_u32_e32 v200, s66, v185
	ds_read_b128 v[132:135], v162
	ds_read_b128 v[136:139], v162 offset:1024
	ds_read_b128 v[158:161], v162 offset:2048
	ds_read_b128 v[162:165], v162 offset:3072
	ds_read_b128 v[188:191], v200
	ds_read_b128 v[192:195], v200 offset:1024
	ds_read_b128 v[196:199], v200 offset:2048
	ds_read_b128 v[200:203], v200 offset:3072
	s_add_u32 s26, s26, 0x80000
	s_addc_u32 s27, s27, 0
	s_mov_b32 m0, s35
	ds_read_b128 v[204:207], v187 offset:32768
	ds_read_b128 v[208:211], v187 offset:33792
	ds_read_b128 v[212:215], v187 offset:34816
	ds_read_b128 v[216:219], v187 offset:35840
	ds_read_b128 v[220:223], v187 offset:36864
	ds_read_b128 v[224:227], v187 offset:37888
	ds_read_b128 v[228:231], v187 offset:38912
	ds_read_b128 v[232:235], v187 offset:39936
	global_load_lds_dwordx4 v0, s[26:27]
	s_mov_b32 m0, s42
	s_nop 0
	global_load_lds_dwordx4 v150, s[26:27]
	s_waitcnt vmcnt(8)
	s_waitcnt lgkmcnt(0)
	s_barrier
	s_setprio 1
	s_waitcnt lgkmcnt(0)
	v_mfma_f32_16x16x32_bf16 v[128:131], v[132:135], v[204:207], v[128:131]
	v_mfma_f32_16x16x32_bf16 v[124:127], v[158:161], v[204:207], v[124:127]
	v_mfma_f32_16x16x32_bf16 v[112:115], v[132:135], v[212:215], v[112:115]
	v_mfma_f32_16x16x32_bf16 v[108:111], v[158:161], v[212:215], v[108:111]
	v_mfma_f32_16x16x32_bf16 v[96:99], v[132:135], v[220:223], v[96:99]
	v_mfma_f32_16x16x32_bf16 v[92:95], v[158:161], v[220:223], v[92:95]
	v_mfma_f32_16x16x32_bf16 v[80:83], v[132:135], v[228:231], v[80:83]
	v_mfma_f32_16x16x32_bf16 v[76:79], v[158:161], v[228:231], v[76:79]
	v_mfma_f32_16x16x32_bf16 v[128:131], v[136:139], v[208:211], v[128:131]
	v_mfma_f32_16x16x32_bf16 v[124:127], v[162:165], v[208:211], v[124:127]
	v_mfma_f32_16x16x32_bf16 v[112:115], v[136:139], v[216:219], v[112:115]
	v_mfma_f32_16x16x32_bf16 v[108:111], v[162:165], v[216:219], v[108:111]
	v_mfma_f32_16x16x32_bf16 v[96:99], v[136:139], v[224:227], v[96:99]
	v_mfma_f32_16x16x32_bf16 v[92:95], v[162:165], v[224:227], v[92:95]
	v_mfma_f32_16x16x32_bf16 v[80:83], v[136:139], v[232:235], v[80:83]
	v_mfma_f32_16x16x32_bf16 v[76:79], v[162:165], v[232:235], v[76:79]
	s_setprio 0
	s_setprio 1
	v_mfma_f32_16x16x32_bf16 v[120:123], v[188:191], v[204:207], v[120:123]
	v_mfma_f32_16x16x32_bf16 v[116:119], v[196:199], v[204:207], v[116:119]
	v_mfma_f32_16x16x32_bf16 v[104:107], v[188:191], v[212:215], v[104:107]
	v_mfma_f32_16x16x32_bf16 v[100:103], v[196:199], v[212:215], v[100:103]
	v_mfma_f32_16x16x32_bf16 v[88:91], v[188:191], v[220:223], v[88:91]
	v_mfma_f32_16x16x32_bf16 v[84:87], v[196:199], v[220:223], v[84:87]
	v_mfma_f32_16x16x32_bf16 v[72:75], v[188:191], v[228:231], v[72:75]
	v_mfma_f32_16x16x32_bf16 v[68:71], v[196:199], v[228:231], v[68:71]
	v_mfma_f32_16x16x32_bf16 v[120:123], v[192:195], v[208:211], v[120:123]
	v_mfma_f32_16x16x32_bf16 v[116:119], v[200:203], v[208:211], v[116:119]
	v_mfma_f32_16x16x32_bf16 v[104:107], v[192:195], v[216:219], v[104:107]
	v_mfma_f32_16x16x32_bf16 v[100:103], v[200:203], v[216:219], v[100:103]
	v_mfma_f32_16x16x32_bf16 v[88:91], v[192:195], v[224:227], v[88:91]
	v_mfma_f32_16x16x32_bf16 v[84:87], v[200:203], v[224:227], v[84:87]
	v_mfma_f32_16x16x32_bf16 v[72:75], v[192:195], v[232:235], v[72:75]
	v_mfma_f32_16x16x32_bf16 v[68:71], v[200:203], v[232:235], v[68:71]
	s_setprio 0
	s_barrier
; #define PG8_STAGE(bufoff, gbase, voff) do { _Pragma("unroll") for (int _i = 0; _i < 2; ++_i) \
;         __builtin_amdgcn_global_load_lds((const unsigned*)((const char*)(gbase) + (voff)[_i]), (PG8_LAS unsigned*)(lds + (bufoff) + ldsw + _i * 8192), 16, 0, 0); } while (0)
; #define PG8_LDA(dst, b, h) do { _Pragma("unroll") for (int m = 0; m < 4; ++m) _Pragma("unroll") for (int k = 0; k < 2; ++k) dst[m][k] = *(const PG8_LAS bf16x8*)(lds + PG8_SA(b, h) + aoff + m * 2048 + k * 1024); } while (0)
; #define PG8_MMA(ai, bj, At, Bt) do { __builtin_amdgcn_s_setprio(1); _Pragma("unroll") for (int m = 0; m < 4; ++m) _Pragma("unroll") for (int n = 0; n < 2; ++n) _Pragma("unroll") for (int k = 0; k < 2; ++k) \
;         acc[ai][bj][m][n] = __builtin_amdgcn_mfma_f32_16x16x32_bf16(Bt[n][k], At[m][k], acc[ai][bj][m][n], 0, 0, 0); __builtin_amdgcn_s_setprio(0); } while (0)
; #define PG8_WAIT_V(n) asm volatile("s_waitcnt vmcnt(" #n ")" ::: "memory")
; #define PG8_WAIT_L(n) asm volatile("s_waitcnt lgkmcnt(" #n ")" ::: "memory")
; #define PG8_BAR __builtin_amdgcn_s_barrier()
; #define PG8_SCHED __builtin_amdgcn_sched_barrier(0)
; template <class Epi, class Sched, bool ALIGN_EPI = false, bool SP2 = false>
; __device__ __forceinline__ void gemm_phase(PG8_LAS unsigned char* lds, const Gemm g, const Sched& S, const Epi& E) {
;     ...
;             PG8_LDA(At, 1, 1); PG8_STAGE(PG8_SB(1, 0), b3, voffB); PG8_STAGE(PG8_SB(1, 1), b3 + hstep, voffB); PG8_STAGE(PG8_SA(1, 0), a3, voffA);
;             PG8_WAIT_V(8); PG8_WAIT_L(0); PG8_BAR; PG8_MMA(1, 0, At, B0); PG8_MMA(1, 1, At, B1); PG8_BAR; PG8_SCHED;
;     ...
;         if constexpr (ALIGN_EPI) { if (wr == 0) PG8_BAR; }
	s_add_i32 s26, s65, s31
	v_lshl_add_u64 v[166:167], v[166:167], 0, s[36:37]
	s_mov_b32 m0, s26
	ds_read_b128 v[204:207], v187 offset:49152
	ds_read_b128 v[208:211], v187 offset:50176
	ds_read_b128 v[212:215], v187 offset:51200
	ds_read_b128 v[216:219], v187 offset:52224
	ds_read_b128 v[220:223], v187 offset:53248
	ds_read_b128 v[224:227], v187 offset:54272
	ds_read_b128 v[228:231], v187 offset:55296
	ds_read_b128 v[232:235], v187 offset:56320
	global_load_lds_dwordx4 v[166:167], off
	s_add_i32 m0, s26, 0x2000
	s_add_u32 s24, s24, 0x80080
	v_lshl_add_u64 v[166:167], v[236:237], 0, s[36:37]
	s_addc_u32 s25, s25, 0
	s_add_i32 s26, s66, s31
	global_load_lds_dwordx4 v[166:167], off
	s_mov_b32 m0, s26
	s_nop 0
	global_load_lds_dwordx4 v2, s[24:25]
	s_add_i32 m0, s26, 0x2000
	s_nop 0
	global_load_lds_dwordx4 v152, s[24:25]
	v_lshl_add_u64 v[166:167], v[238:239], 0, s[36:37]
	s_mov_b32 m0, s44
	s_nop 0
	global_load_lds_dwordx4 v[166:167], off
	v_lshl_add_u64 v[166:167], v[240:241], 0, s[36:37]
	s_mov_b32 m0, s45
	s_nop 0
	global_load_lds_dwordx4 v[166:167], off
	s_waitcnt vmcnt(8)
	s_waitcnt lgkmcnt(0)
	s_barrier
	s_setprio 1
	s_waitcnt lgkmcnt(0)
	v_mfma_f32_16x16x32_bf16 v[64:67], v[132:135], v[204:207], v[64:67]
	v_mfma_f32_16x16x32_bf16 v[60:63], v[158:161], v[204:207], v[60:63]
	v_mfma_f32_16x16x32_bf16 v[48:51], v[132:135], v[212:215], v[48:51]
	v_mfma_f32_16x16x32_bf16 v[44:47], v[158:161], v[212:215], v[44:47]
	v_mfma_f32_16x16x32_bf16 v[32:35], v[132:135], v[220:223], v[32:35]
	v_mfma_f32_16x16x32_bf16 v[28:31], v[158:161], v[220:223], v[28:31]
	v_mfma_f32_16x16x32_bf16 v[16:19], v[132:135], v[228:231], v[16:19]
	v_mfma_f32_16x16x32_bf16 v[12:15], v[158:161], v[228:231], v[12:15]
	v_mfma_f32_16x16x32_bf16 v[64:67], v[136:139], v[208:211], v[64:67]
	v_mfma_f32_16x16x32_bf16 v[60:63], v[162:165], v[208:211], v[60:63]
	v_mfma_f32_16x16x32_bf16 v[48:51], v[136:139], v[216:219], v[48:51]
	v_mfma_f32_16x16x32_bf16 v[44:47], v[162:165], v[216:219], v[44:47]
	v_mfma_f32_16x16x32_bf16 v[32:35], v[136:139], v[224:227], v[32:35]
	v_mfma_f32_16x16x32_bf16 v[28:31], v[162:165], v[224:227], v[28:31]
	v_mfma_f32_16x16x32_bf16 v[16:19], v[136:139], v[232:235], v[16:19]
	v_mfma_f32_16x16x32_bf16 v[12:15], v[162:165], v[232:235], v[12:15]
	s_setprio 0
	s_setprio 1
	v_mfma_f32_16x16x32_bf16 v[56:59], v[188:191], v[204:207], v[56:59]
	v_mfma_f32_16x16x32_bf16 v[52:55], v[196:199], v[204:207], v[52:55]
	v_mfma_f32_16x16x32_bf16 v[40:43], v[188:191], v[212:215], v[40:43]
	v_mfma_f32_16x16x32_bf16 v[36:39], v[196:199], v[212:215], v[36:39]
	v_mfma_f32_16x16x32_bf16 v[24:27], v[188:191], v[220:223], v[24:27]
	v_mfma_f32_16x16x32_bf16 v[20:23], v[196:199], v[220:223], v[20:23]
	v_mfma_f32_16x16x32_bf16 v[8:11], v[188:191], v[228:231], v[8:11]
	v_mfma_f32_16x16x32_bf16 v[4:7], v[196:199], v[228:231], v[4:7]
	v_mfma_f32_16x16x32_bf16 v[56:59], v[192:195], v[208:211], v[56:59]
	v_mfma_f32_16x16x32_bf16 v[52:55], v[200:203], v[208:211], v[52:55]
	v_mfma_f32_16x16x32_bf16 v[40:43], v[192:195], v[216:219], v[40:43]
	v_mfma_f32_16x16x32_bf16 v[36:39], v[200:203], v[216:219], v[36:39]
	v_mfma_f32_16x16x32_bf16 v[24:27], v[192:195], v[224:227], v[24:27]
	v_mfma_f32_16x16x32_bf16 v[20:23], v[200:203], v[224:227], v[20:23]
	v_mfma_f32_16x16x32_bf16 v[8:11], v[192:195], v[232:235], v[8:11]
	v_mfma_f32_16x16x32_bf16 v[4:7], v[200:203], v[232:235], v[4:7]
	s_setprio 0
	s_barrier
	s_add_i32 s64, s64, 2
	s_add_u32 s22, s22, 0x100
	s_addc_u32 s23, s23, 0
	s_add_u32 s57, s57, 0x100
	s_addc_u32 s63, s63, 0
	s_cmp_gt_u32 s64, 29
	s_cbranch_scc0 .LBB0_483
	s_and_b64 vcc, exec, s[8:9]
	s_cbranch_vccz .LBB0_486
	s_barrier

; #define PG8_STAGE(bufoff, gbase, voff) do { _Pragma("unroll") for (int _i = 0; _i < 2; ++_i) \
;         __builtin_amdgcn_global_load_lds((const unsigned*)((const char*)(gbase) + (voff)[_i]), (PG8_LAS unsigned*)(lds + (bufoff) + ldsw + _i * 8192), 16, 0, 0); } while (0)
; #define PG8_LDA(dst, b, h) do { _Pragma("unroll") for (int m = 0; m < 4; ++m) _Pragma("unroll") for (int k = 0; k < 2; ++k) dst[m][k] = *(const PG8_LAS bf16x8*)(lds + PG8_SA(b, h) + aoff + m * 2048 + k * 1024); } while (0)
; #define PG8_LDB(dst, b, h) do { _Pragma("unroll") for (int n = 0; n < 2; ++n) _Pragma("unroll") for (int k = 0; k < 2; ++k) dst[n][k] = *(const PG8_LAS bf16x8*)(lds + PG8_SB(b, h) + boff + n * 2048 + k * 1024); } while (0)
; #define PG8_MMA(ai, bj, At, Bt) do { __builtin_amdgcn_s_setprio(1); _Pragma("unroll") for (int m = 0; m < 4; ++m) _Pragma("unroll") for (int n = 0; n < 2; ++n) _Pragma("unroll") for (int k = 0; k < 2; ++k) \
;         acc[ai][bj][m][n] = __builtin_amdgcn_mfma_f32_16x16x32_bf16(Bt[n][k], At[m][k], acc[ai][bj][m][n], 0, 0, 0); __builtin_amdgcn_s_setprio(0); } while (0)
; #define PG8_WAIT_V(n) asm volatile("s_waitcnt vmcnt(" #n ")" ::: "memory")
; #define PG8_WAIT_L(n) asm volatile("s_waitcnt lgkmcnt(" #n ")" ::: "memory")
; template <class Epi, class Sched, bool ALIGN_EPI = false, bool SP2 = false>
; __device__ __forceinline__ void gemm_phase(PG8_LAS unsigned char* lds, const Gemm g, const Sched& S, const Epi& E) {
;     ...
;             const bool last = (t == nt - 2);
;             const char* a1 = cA + (size_t)(t + 1) * kstep;
;             const char* a2 = last ? nA : cA + (size_t)(t + 2) * kstep; const char* b2 = last ? nB : cB + (size_t)(t + 2) * kstep;
;             const char* a3 = a2 + kstep; const char* b3 = b2 + kstep;
;             if (last && has_next) S.a_ready(nxt);
;             if constexpr (SP2) {
;             PG8_LDB(B0, 0, 0); PG8_LDB(B1, 0, 1); PG8_SCHED; PG8_LDA(At, 0, 0); PG8_STAGE(PG8_SA(1, 1), a1 + hstep, voffA);
;             PG8_WAIT_V(8); PG8_WAIT_L(0); PG8_BAR; PG8_MMA(0, 0, At, B0); PG8_MMA(0, 1, At, B1); PG8_BAR; PG8_SCHED;
;             PG8_LDA(At, 0, 1); PG8_STAGE(PG8_SB(0, 0), b2, voffB); PG8_STAGE(PG8_SB(0, 1), b2 + hstep, voffB); PG8_STAGE(PG8_SA(0, 0), a2, voffA);
;             PG8_WAIT_V(8); PG8_WAIT_L(0); PG8_BAR; PG8_MMA(1, 0, At, B0); PG8_MMA(1, 1, At, B1); PG8_BAR; PG8_SCHED;
.LBB0_567:
	s_add_u32 s20, s18, 0xfff80080
	s_addc_u32 s21, s19, -1
	s_add_i32 s63, 0, 0x10000
	s_cmp_eq_u32 s57, 28
	s_cselect_b32 s23, s11, s21
	s_cselect_b32 s22, s45, s20
	v_add_u32_e32 v150, s63, v153
	s_cselect_b32 s21, s9, s56
	s_cselect_b32 s20, s50, s51
	s_add_i32 s66, 0, 0x14000
	ds_read_b128 v[184:187], v150
	ds_read_b128 v[188:191], v150 offset:1024
	ds_read_b128 v[192:195], v150 offset:2048
	ds_read_b128 v[196:199], v150 offset:3072
	v_add_u32_e32 v150, s66, v153
	ds_read_b128 v[200:203], v150
	ds_read_b128 v[204:207], v150 offset:1024
	ds_read_b128 v[208:211], v150 offset:2048
	ds_read_b128 v[212:215], v150 offset:3072
	s_add_i32 m0, s29, 0xc000
	ds_read_b128 v[216:219], v155
	ds_read_b128 v[220:223], v155 offset:1024
	ds_read_b128 v[224:227], v155 offset:2048
	ds_read_b128 v[228:231], v155 offset:3072
	ds_read_b128 v[232:235], v155 offset:4096
	ds_read_b128 v[236:239], v155 offset:5120
	ds_read_b128 v[240:243], v155 offset:6144
	ds_read_b128 v[244:247], v155 offset:7168
	global_load_lds_dwordx4 v136, s[18:19]
	s_add_i32 m0, s29, 0xe000
	s_nop 0
	global_load_lds_dwordx4 v138, s[18:19]
	s_waitcnt vmcnt(8)
	s_waitcnt lgkmcnt(0)
	s_barrier
	s_setprio 1
	s_waitcnt lgkmcnt(0)
	v_mfma_f32_16x16x32_bf16 v[128:131], v[184:187], v[216:219], v[128:131]
	v_mfma_f32_16x16x32_bf16 v[120:123], v[192:195], v[216:219], v[120:123]
	v_mfma_f32_16x16x32_bf16 v[112:115], v[184:187], v[224:227], v[112:115]
	v_mfma_f32_16x16x32_bf16 v[104:107], v[192:195], v[224:227], v[104:107]
	v_mfma_f32_16x16x32_bf16 v[96:99], v[184:187], v[232:235], v[96:99]
	v_mfma_f32_16x16x32_bf16 v[88:91], v[192:195], v[232:235], v[88:91]
	v_mfma_f32_16x16x32_bf16 v[80:83], v[184:187], v[240:243], v[80:83]
	v_mfma_f32_16x16x32_bf16 v[72:75], v[192:195], v[240:243], v[72:75]
	v_mfma_f32_16x16x32_bf16 v[128:131], v[188:191], v[220:223], v[128:131]
	v_mfma_f32_16x16x32_bf16 v[120:123], v[196:199], v[220:223], v[120:123]
	v_mfma_f32_16x16x32_bf16 v[112:115], v[188:191], v[228:231], v[112:115]
	v_mfma_f32_16x16x32_bf16 v[104:107], v[196:199], v[228:231], v[104:107]
	v_mfma_f32_16x16x32_bf16 v[96:99], v[188:191], v[236:239], v[96:99]
	v_mfma_f32_16x16x32_bf16 v[88:91], v[196:199], v[236:239], v[88:91]
	v_mfma_f32_16x16x32_bf16 v[80:83], v[188:191], v[244:247], v[80:83]
	v_mfma_f32_16x16x32_bf16 v[72:75], v[196:199], v[244:247], v[72:75]
	s_setprio 0
	s_setprio 1
	v_mfma_f32_16x16x32_bf16 v[124:127], v[200:203], v[216:219], v[124:127]
	v_mfma_f32_16x16x32_bf16 v[116:119], v[208:211], v[216:219], v[116:119]
	v_mfma_f32_16x16x32_bf16 v[108:111], v[200:203], v[224:227], v[108:111]
	v_mfma_f32_16x16x32_bf16 v[100:103], v[208:211], v[224:227], v[100:103]
	v_mfma_f32_16x16x32_bf16 v[92:95], v[200:203], v[232:235], v[92:95]
	v_mfma_f32_16x16x32_bf16 v[84:87], v[208:211], v[232:235], v[84:87]
	v_mfma_f32_16x16x32_bf16 v[76:79], v[200:203], v[240:243], v[76:79]
	v_mfma_f32_16x16x32_bf16 v[68:71], v[208:211], v[240:243], v[68:71]
	v_mfma_f32_16x16x32_bf16 v[124:127], v[204:207], v[220:223], v[124:127]
	v_mfma_f32_16x16x32_bf16 v[116:119], v[212:215], v[220:223], v[116:119]
	v_mfma_f32_16x16x32_bf16 v[108:111], v[204:207], v[228:231], v[108:111]
	v_mfma_f32_16x16x32_bf16 v[100:103], v[212:215], v[228:231], v[100:103]
	v_mfma_f32_16x16x32_bf16 v[92:95], v[204:207], v[236:239], v[92:95]
	v_mfma_f32_16x16x32_bf16 v[84:87], v[212:215], v[236:239], v[84:87]
	v_mfma_f32_16x16x32_bf16 v[76:79], v[204:207], v[244:247], v[76:79]
	v_mfma_f32_16x16x32_bf16 v[68:71], v[212:215], v[244:247], v[68:71]
	s_setprio 0
	s_barrier
	s_add_i32 s63, s63, s27
	v_lshl_add_u64 v[150:151], s[20:21], 0, v[2:3]
	s_mov_b32 m0, s63
	ds_read_b128 v[216:219], v155 offset:16384
	ds_read_b128 v[220:223], v155 offset:17408
	ds_read_b128 v[224:227], v155 offset:18432
	ds_read_b128 v[228:231], v155 offset:19456
	ds_read_b128 v[232:235], v155 offset:20480
	ds_read_b128 v[236:239], v155 offset:21504
	ds_read_b128 v[240:243], v155 offset:22528
	ds_read_b128 v[244:247], v155 offset:23552
	global_load_lds_dwordx4 v[150:151], off
	s_add_i32 m0, s63, 0x2000
	s_add_u32 s64, s20, 0x80000
	v_lshl_add_u64 v[166:167], s[20:21], 0, v[0:1]
	s_addc_u32 s65, s21, 0
	s_add_i32 s63, s66, s27
	global_load_lds_dwordx4 v[166:167], off
	s_mov_b32 m0, s63
	v_lshl_add_u64 v[250:251], s[22:23], 0, v[132:133]
	global_load_lds_dwordx4 v2, s[64:65]
	s_add_i32 m0, s63, 0x2000
	s_nop 0
	global_load_lds_dwordx4 v0, s[64:65]
	v_lshl_add_u64 v[248:249], s[22:23], 0, v[134:135]
	s_mov_b32 m0, s29
	s_nop 0
	global_load_lds_dwordx4 v[248:249], off
	s_mov_b32 m0, s30
	s_nop 0
	global_load_lds_dwordx4 v[250:251], off
	s_waitcnt vmcnt(8)
	s_waitcnt lgkmcnt(0)
	s_barrier
; #define PG8_STAGE(bufoff, gbase, voff) do { _Pragma("unroll") for (int _i = 0; _i < 2; ++_i) \
;         __builtin_amdgcn_global_load_lds((const unsigned*)((const char*)(gbase) + (voff)[_i]), (PG8_LAS unsigned*)(lds + (bufoff) + ldsw + _i * 8192), 16, 0, 0); } while (0)
; #define PG8_LDA(dst, b, h) do { _Pragma("unroll") for (int m = 0; m < 4; ++m) _Pragma("unroll") for (int k = 0; k < 2; ++k) dst[m][k] = *(const PG8_LAS bf16x8*)(lds + PG8_SA(b, h) + aoff + m * 2048 + k * 1024); } while (0)
; #define PG8_LDB(dst, b, h) do { _Pragma("unroll") for (int n = 0; n < 2; ++n) _Pragma("unroll") for (int k = 0; k < 2; ++k) dst[n][k] = *(const PG8_LAS bf16x8*)(lds + PG8_SB(b, h) + boff + n * 2048 + k * 1024); } while (0)
; #define PG8_MMA(ai, bj, At, Bt) do { __builtin_amdgcn_s_setprio(1); _Pragma("unroll") for (int m = 0; m < 4; ++m) _Pragma("unroll") for (int n = 0; n < 2; ++n) _Pragma("unroll") for (int k = 0; k < 2; ++k) \
;         acc[ai][bj][m][n] = __builtin_amdgcn_mfma_f32_16x16x32_bf16(Bt[n][k], At[m][k], acc[ai][bj][m][n], 0, 0, 0); __builtin_amdgcn_s_setprio(0); } while (0)
; #define PG8_WAIT_V(n) asm volatile("s_waitcnt vmcnt(" #n ")" ::: "memory")
; #define PG8_WAIT_L(n) asm volatile("s_waitcnt lgkmcnt(" #n ")" ::: "memory")
; #define PG8_BAR __builtin_amdgcn_s_barrier()
; #define PG8_SCHED __builtin_amdgcn_sched_barrier(0)
; template <class Epi, class Sched, bool ALIGN_EPI = false, bool SP2 = false>
; __device__ __forceinline__ void gemm_phase(PG8_LAS unsigned char* lds, const Gemm g, const Sched& S, const Epi& E) {
;     ...
;             PG8_WAIT_V(8); PG8_WAIT_L(0); PG8_BAR; PG8_MMA(1, 0, At, B0); PG8_MMA(1, 1, At, B1); PG8_BAR; PG8_SCHED;
;             PG8_LDB(B0, 1, 0); PG8_LDB(B1, 1, 1); PG8_SCHED; PG8_LDA(At, 1, 0); PG8_STAGE(PG8_SA(0, 1), a2 + hstep, voffA);
;             PG8_WAIT_V(8); PG8_WAIT_L(0); PG8_BAR; PG8_MMA(0, 0, At, B0); PG8_MMA(0, 1, At, B1); PG8_BAR; PG8_SCHED;
	s_setprio 1
	s_waitcnt lgkmcnt(0)
	v_mfma_f32_16x16x32_bf16 v[64:67], v[184:187], v[216:219], v[64:67]
	v_mfma_f32_16x16x32_bf16 v[56:59], v[192:195], v[216:219], v[56:59]
	v_mfma_f32_16x16x32_bf16 v[48:51], v[184:187], v[224:227], v[48:51]
	v_mfma_f32_16x16x32_bf16 v[40:43], v[192:195], v[224:227], v[40:43]
	v_mfma_f32_16x16x32_bf16 v[32:35], v[184:187], v[232:235], v[32:35]
	v_mfma_f32_16x16x32_bf16 v[24:27], v[192:195], v[232:235], v[24:27]
	v_mfma_f32_16x16x32_bf16 v[16:19], v[184:187], v[240:243], v[16:19]
	v_mfma_f32_16x16x32_bf16 v[8:11], v[192:195], v[240:243], v[8:11]
	v_mfma_f32_16x16x32_bf16 v[64:67], v[188:191], v[220:223], v[64:67]
	v_mfma_f32_16x16x32_bf16 v[56:59], v[196:199], v[220:223], v[56:59]
	v_mfma_f32_16x16x32_bf16 v[48:51], v[188:191], v[228:231], v[48:51]
	v_mfma_f32_16x16x32_bf16 v[40:43], v[196:199], v[228:231], v[40:43]
	v_mfma_f32_16x16x32_bf16 v[32:35], v[188:191], v[236:239], v[32:35]
	v_mfma_f32_16x16x32_bf16 v[24:27], v[196:199], v[236:239], v[24:27]
	v_mfma_f32_16x16x32_bf16 v[16:19], v[188:191], v[244:247], v[16:19]
	v_mfma_f32_16x16x32_bf16 v[8:11], v[196:199], v[244:247], v[8:11]
	s_setprio 0
	s_setprio 1
	v_mfma_f32_16x16x32_bf16 v[60:63], v[200:203], v[216:219], v[60:63]
	v_mfma_f32_16x16x32_bf16 v[52:55], v[208:211], v[216:219], v[52:55]
	v_mfma_f32_16x16x32_bf16 v[44:47], v[200:203], v[224:227], v[44:47]
	v_mfma_f32_16x16x32_bf16 v[36:39], v[208:211], v[224:227], v[36:39]
	v_mfma_f32_16x16x32_bf16 v[28:31], v[200:203], v[232:235], v[28:31]
	v_mfma_f32_16x16x32_bf16 v[20:23], v[208:211], v[232:235], v[20:23]
	v_mfma_f32_16x16x32_bf16 v[12:15], v[200:203], v[240:243], v[12:15]
	v_mfma_f32_16x16x32_bf16 v[4:7], v[208:211], v[240:243], v[4:7]
	v_mfma_f32_16x16x32_bf16 v[60:63], v[204:207], v[220:223], v[60:63]
	v_mfma_f32_16x16x32_bf16 v[52:55], v[212:215], v[220:223], v[52:55]
	v_mfma_f32_16x16x32_bf16 v[44:47], v[204:207], v[228:231], v[44:47]
	v_mfma_f32_16x16x32_bf16 v[36:39], v[212:215], v[228:231], v[36:39]
	v_mfma_f32_16x16x32_bf16 v[28:31], v[204:207], v[236:239], v[28:31]
	v_mfma_f32_16x16x32_bf16 v[20:23], v[212:215], v[236:239], v[20:23]
	v_mfma_f32_16x16x32_bf16 v[12:15], v[204:207], v[244:247], v[12:15]
	v_mfma_f32_16x16x32_bf16 v[4:7], v[212:215], v[244:247], v[4:7]
	s_setprio 0
	s_barrier
	s_add_i32 s63, 0, 0x18000
	v_add_u32_e32 v161, s63, v153
	s_add_i32 s64, 0, 0x1c000
	ds_read_b128 v[184:187], v161
	ds_read_b128 v[188:191], v161 offset:1024
	ds_read_b128 v[192:195], v161 offset:2048
	ds_read_b128 v[196:199], v161 offset:3072
	v_add_u32_e32 v161, s64, v153
	ds_read_b128 v[200:203], v161
	ds_read_b128 v[204:207], v161 offset:1024
	ds_read_b128 v[208:211], v161 offset:2048
	ds_read_b128 v[212:215], v161 offset:3072
	s_add_u32 s22, s22, 0x80000
	s_addc_u32 s23, s23, 0
	s_mov_b32 m0, s31
	ds_read_b128 v[216:219], v155 offset:32768
	ds_read_b128 v[220:223], v155 offset:33792
	ds_read_b128 v[224:227], v155 offset:34816
	ds_read_b128 v[228:231], v155 offset:35840
	ds_read_b128 v[232:235], v155 offset:36864
	ds_read_b128 v[236:239], v155 offset:37888
	ds_read_b128 v[240:243], v155 offset:38912
	ds_read_b128 v[244:247], v155 offset:39936
	global_load_lds_dwordx4 v134, s[22:23]
	s_mov_b32 m0, s34
	s_nop 0
	global_load_lds_dwordx4 v132, s[22:23]
	s_waitcnt vmcnt(8)
	s_waitcnt lgkmcnt(0)
	s_barrier
	s_setprio 1
	s_waitcnt lgkmcnt(0)
	v_mfma_f32_16x16x32_bf16 v[128:131], v[184:187], v[216:219], v[128:131]
	v_mfma_f32_16x16x32_bf16 v[120:123], v[192:195], v[216:219], v[120:123]
	v_mfma_f32_16x16x32_bf16 v[112:115], v[184:187], v[224:227], v[112:115]
	v_mfma_f32_16x16x32_bf16 v[104:107], v[192:195], v[224:227], v[104:107]
	v_mfma_f32_16x16x32_bf16 v[96:99], v[184:187], v[232:235], v[96:99]
	v_mfma_f32_16x16x32_bf16 v[88:91], v[192:195], v[232:235], v[88:91]
	v_mfma_f32_16x16x32_bf16 v[80:83], v[184:187], v[240:243], v[80:83]
	v_mfma_f32_16x16x32_bf16 v[72:75], v[192:195], v[240:243], v[72:75]
	v_mfma_f32_16x16x32_bf16 v[128:131], v[188:191], v[220:223], v[128:131]
	v_mfma_f32_16x16x32_bf16 v[120:123], v[196:199], v[220:223], v[120:123]
	v_mfma_f32_16x16x32_bf16 v[112:115], v[188:191], v[228:231], v[112:115]
	v_mfma_f32_16x16x32_bf16 v[104:107], v[196:199], v[228:231], v[104:107]
	v_mfma_f32_16x16x32_bf16 v[96:99], v[188:191], v[236:239], v[96:99]
	v_mfma_f32_16x16x32_bf16 v[88:91], v[196:199], v[236:239], v[88:91]
	v_mfma_f32_16x16x32_bf16 v[80:83], v[188:191], v[244:247], v[80:83]
	v_mfma_f32_16x16x32_bf16 v[72:75], v[196:199], v[244:247], v[72:75]
	s_setprio 0
	s_setprio 1
	v_mfma_f32_16x16x32_bf16 v[124:127], v[200:203], v[216:219], v[124:127]
	v_mfma_f32_16x16x32_bf16 v[116:119], v[208:211], v[216:219], v[116:119]
	v_mfma_f32_16x16x32_bf16 v[108:111], v[200:203], v[224:227], v[108:111]
	v_mfma_f32_16x16x32_bf16 v[100:103], v[208:211], v[224:227], v[100:103]
	v_mfma_f32_16x16x32_bf16 v[92:95], v[200:203], v[232:235], v[92:95]
	v_mfma_f32_16x16x32_bf16 v[84:87], v[208:211], v[232:235], v[84:87]
	v_mfma_f32_16x16x32_bf16 v[76:79], v[200:203], v[240:243], v[76:79]
	v_mfma_f32_16x16x32_bf16 v[68:71], v[208:211], v[240:243], v[68:71]
	v_mfma_f32_16x16x32_bf16 v[124:127], v[204:207], v[220:223], v[124:127]
	v_mfma_f32_16x16x32_bf16 v[116:119], v[212:215], v[220:223], v[116:119]
	v_mfma_f32_16x16x32_bf16 v[108:111], v[204:207], v[228:231], v[108:111]
	v_mfma_f32_16x16x32_bf16 v[100:103], v[212:215], v[228:231], v[100:103]
	v_mfma_f32_16x16x32_bf16 v[92:95], v[204:207], v[236:239], v[92:95]
	v_mfma_f32_16x16x32_bf16 v[84:87], v[212:215], v[236:239], v[84:87]
	v_mfma_f32_16x16x32_bf16 v[76:79], v[204:207], v[244:247], v[76:79]
	v_mfma_f32_16x16x32_bf16 v[68:71], v[212:215], v[244:247], v[68:71]
	s_setprio 0
	s_barrier
; #define PG8_STAGE(bufoff, gbase, voff) do { _Pragma("unroll") for (int _i = 0; _i < 2; ++_i) \
;         __builtin_amdgcn_global_load_lds((const unsigned*)((const char*)(gbase) + (voff)[_i]), (PG8_LAS unsigned*)(lds + (bufoff) + ldsw + _i * 8192), 16, 0, 0); } while (0)
; #define PG8_LDA(dst, b, h) do { _Pragma("unroll") for (int m = 0; m < 4; ++m) _Pragma("unroll") for (int k = 0; k < 2; ++k) dst[m][k] = *(const PG8_LAS bf16x8*)(lds + PG8_SA(b, h) + aoff + m * 2048 + k * 1024); } while (0)
; #define PG8_MMA(ai, bj, At, Bt) do { __builtin_amdgcn_s_setprio(1); _Pragma("unroll") for (int m = 0; m < 4; ++m) _Pragma("unroll") for (int n = 0; n < 2; ++n) _Pragma("unroll") for (int k = 0; k < 2; ++k) \
;         acc[ai][bj][m][n] = __builtin_amdgcn_mfma_f32_16x16x32_bf16(Bt[n][k], At[m][k], acc[ai][bj][m][n], 0, 0, 0); __builtin_amdgcn_s_setprio(0); } while (0)
; #define PG8_WAIT_V(n) asm volatile("s_waitcnt vmcnt(" #n ")" ::: "memory")
; #define PG8_WAIT_L(n) asm volatile("s_waitcnt lgkmcnt(" #n ")" ::: "memory")
; #define PG8_BAR __builtin_amdgcn_s_barrier()
; #define PG8_SCHED __builtin_amdgcn_sched_barrier(0)
; template <class Epi, class Sched, bool ALIGN_EPI = false, bool SP2 = false>
; __device__ __forceinline__ void gemm_phase(PG8_LAS unsigned char* lds, const Gemm g, const Sched& S, const Epi& E) {
;     ...
;             PG8_LDA(At, 1, 1); PG8_STAGE(PG8_SB(1, 0), b3, voffB); PG8_STAGE(PG8_SB(1, 1), b3 + hstep, voffB); PG8_STAGE(PG8_SA(1, 0), a3, voffA);
;             PG8_WAIT_V(8); PG8_WAIT_L(0); PG8_BAR; PG8_MMA(1, 0, At, B0); PG8_MMA(1, 1, At, B1); PG8_BAR; PG8_SCHED;
;     ...
;         if constexpr (ALIGN_EPI) { if (wr == 0) PG8_BAR; }
	s_add_i32 s22, s63, s27
	v_lshl_add_u64 v[150:151], v[150:151], 0, s[36:37]
	s_mov_b32 m0, s22
	ds_read_b128 v[216:219], v155 offset:49152
	ds_read_b128 v[220:223], v155 offset:50176
	ds_read_b128 v[224:227], v155 offset:51200
	ds_read_b128 v[228:231], v155 offset:52224
	ds_read_b128 v[232:235], v155 offset:53248
	ds_read_b128 v[236:239], v155 offset:54272
	ds_read_b128 v[240:243], v155 offset:55296
	ds_read_b128 v[244:247], v155 offset:56320
	global_load_lds_dwordx4 v[150:151], off
	s_add_i32 m0, s22, 0x2000
	s_add_u32 s20, s20, 0x80080
	v_lshl_add_u64 v[150:151], v[166:167], 0, s[36:37]
	s_addc_u32 s21, s21, 0
	s_add_i32 s22, s64, s27
	global_load_lds_dwordx4 v[150:151], off
	s_mov_b32 m0, s22
	s_nop 0
	global_load_lds_dwordx4 v2, s[20:21]
	s_add_i32 m0, s22, 0x2000
	s_nop 0
	global_load_lds_dwordx4 v0, s[20:21]
	v_lshl_add_u64 v[150:151], v[248:249], 0, s[36:37]
	s_mov_b32 m0, s35
	s_nop 0
	global_load_lds_dwordx4 v[150:151], off
	v_lshl_add_u64 v[150:151], v[250:251], 0, s[36:37]
	s_mov_b32 m0, s42
	s_nop 0
	global_load_lds_dwordx4 v[150:151], off
	s_waitcnt vmcnt(8)
	s_waitcnt lgkmcnt(0)
	s_barrier
	s_setprio 1
	s_waitcnt lgkmcnt(0)
	v_mfma_f32_16x16x32_bf16 v[64:67], v[184:187], v[216:219], v[64:67]
	v_mfma_f32_16x16x32_bf16 v[56:59], v[192:195], v[216:219], v[56:59]
	v_mfma_f32_16x16x32_bf16 v[48:51], v[184:187], v[224:227], v[48:51]
	v_mfma_f32_16x16x32_bf16 v[40:43], v[192:195], v[224:227], v[40:43]
	v_mfma_f32_16x16x32_bf16 v[32:35], v[184:187], v[232:235], v[32:35]
	v_mfma_f32_16x16x32_bf16 v[24:27], v[192:195], v[232:235], v[24:27]
	v_mfma_f32_16x16x32_bf16 v[16:19], v[184:187], v[240:243], v[16:19]
	v_mfma_f32_16x16x32_bf16 v[8:11], v[192:195], v[240:243], v[8:11]
	v_mfma_f32_16x16x32_bf16 v[64:67], v[188:191], v[220:223], v[64:67]
	v_mfma_f32_16x16x32_bf16 v[56:59], v[196:199], v[220:223], v[56:59]
	v_mfma_f32_16x16x32_bf16 v[48:51], v[188:191], v[228:231], v[48:51]
	v_mfma_f32_16x16x32_bf16 v[40:43], v[196:199], v[228:231], v[40:43]
	v_mfma_f32_16x16x32_bf16 v[32:35], v[188:191], v[236:239], v[32:35]
	v_mfma_f32_16x16x32_bf16 v[24:27], v[196:199], v[236:239], v[24:27]
	v_mfma_f32_16x16x32_bf16 v[16:19], v[188:191], v[244:247], v[16:19]
	v_mfma_f32_16x16x32_bf16 v[8:11], v[196:199], v[244:247], v[8:11]
	s_setprio 0
	s_setprio 1
	v_mfma_f32_16x16x32_bf16 v[60:63], v[200:203], v[216:219], v[60:63]
	v_mfma_f32_16x16x32_bf16 v[52:55], v[208:211], v[216:219], v[52:55]
	v_mfma_f32_16x16x32_bf16 v[44:47], v[200:203], v[224:227], v[44:47]
	v_mfma_f32_16x16x32_bf16 v[36:39], v[208:211], v[224:227], v[36:39]
	v_mfma_f32_16x16x32_bf16 v[28:31], v[200:203], v[232:235], v[28:31]
	v_mfma_f32_16x16x32_bf16 v[20:23], v[208:211], v[232:235], v[20:23]
	v_mfma_f32_16x16x32_bf16 v[12:15], v[200:203], v[240:243], v[12:15]
	v_mfma_f32_16x16x32_bf16 v[4:7], v[208:211], v[240:243], v[4:7]
	v_mfma_f32_16x16x32_bf16 v[60:63], v[204:207], v[220:223], v[60:63]
	v_mfma_f32_16x16x32_bf16 v[52:55], v[212:215], v[220:223], v[52:55]
	v_mfma_f32_16x16x32_bf16 v[44:47], v[204:207], v[228:231], v[44:47]
	v_mfma_f32_16x16x32_bf16 v[36:39], v[212:215], v[228:231], v[36:39]
	v_mfma_f32_16x16x32_bf16 v[28:31], v[204:207], v[236:239], v[28:31]
	v_mfma_f32_16x16x32_bf16 v[20:23], v[212:215], v[236:239], v[20:23]
	v_mfma_f32_16x16x32_bf16 v[12:15], v[204:207], v[244:247], v[12:15]
	v_mfma_f32_16x16x32_bf16 v[4:7], v[212:215], v[244:247], v[4:7]
	s_setprio 0
	s_barrier
	s_add_i32 s57, s57, 2
	s_add_u32 s18, s18, 0x100
	s_addc_u32 s19, s19, 0
	s_add_u32 s51, s51, 0x100
	s_addc_u32 s56, s56, 0
	s_cmp_gt_u32 s57, 29
	s_cbranch_scc0 .LBB0_567
	s_and_b64 vcc, exec, s[6:7]
	s_cbranch_vccz .LBB0_570
	s_barrier
